# GEMM K-loops: first K-tile peeled with inline-zero C on first-touch MFMAs; per-tile accumulator zeroing removed
# speedup vs baseline: 1.0090x; 1.0075x over previous
.LBB0_214:
	s_ashr_i32 s29, s28, 31
	s_lshl_b64 s[30:31], s[28:29], 19
	s_add_u32 s30, s88, s30
	s_addc_u32 s31, s89, s31
	s_and_b64 s[34:35], s[8:9], exec
	s_cselect_b32 s1, s31, s11
	s_cselect_b32 s29, s30, s10
	s_ashr_i32 s27, s26, 31
	s_lshl_b64 s[34:35], s[26:27], 19
	s_add_u32 s34, s19, s34
	s_addc_u32 s35, s25, s35
	s_and_b64 s[36:37], s[8:9], exec
	s_cselect_b32 s27, s35, s3
	s_cselect_b32 s58, s34, s2
	s_add_u32 s10, s10, 0x40080
	s_addc_u32 s11, s11, 0
	s_add_u32 s59, s2, 0x100
	s_addc_u32 s60, s3, 0
	s_mov_b32 s61, -2
	ds_read_b128 v[148:151], v156
	ds_read_b128 v[160:163], v156 offset:1024
	ds_read_b128 v[164:167], v156 offset:2048
	ds_read_b128 v[168:171], v156 offset:3072
	ds_read_b128 v[172:175], v157
	ds_read_b128 v[176:179], v157 offset:1024
	ds_read_b128 v[180:183], v157 offset:2048
	ds_read_b128 v[184:187], v157 offset:3072
	s_add_u32 s2, s10, 0xfffc0080
	s_addc_u32 s3, s11, -1
	s_cmp_eq_u32 s61, 12
	s_cselect_b32 s37, s1, s3
	s_cselect_b32 s36, s29, s2
	s_cselect_b32 s3, s27, s60
	s_cselect_b32 s2, s58, s59
	v_lshl_add_u64 v[212:213], s[10:11], 0, v[140:141]
	s_add_i32 m0, s38, 0xc000
	ds_read_b128 v[188:191], v158
	ds_read_b128 v[192:195], v158 offset:1024
	ds_read_b128 v[196:199], v158 offset:2048
	ds_read_b128 v[200:203], v158 offset:3072
	ds_read_b128 v[204:207], v158 offset:4096
	ds_read_b128 v[208:211], v158 offset:5120
	ds_read_b128 v[216:219], v158 offset:6144
	ds_read_b128 v[220:223], v158 offset:7168
	global_load_lds_dwordx4 v[212:213], off
	v_lshl_add_u64 v[212:213], s[10:11], 0, v[142:143]
	s_add_i32 m0, s38, 0xe000
	s_nop 0
	global_load_lds_dwordx4 v[212:213], off
	s_waitcnt vmcnt(8)
	s_waitcnt lgkmcnt(0)
	s_barrier
	s_setprio 1
	s_waitcnt lgkmcnt(0)
	v_mfma_f32_16x16x32_bf16 v[124:127], v[148:151], v[188:191], 0
	v_mfma_f32_16x16x32_bf16 v[120:123], v[164:167], v[188:191], 0
	v_mfma_f32_16x16x32_bf16 v[108:111], v[148:151], v[196:199], 0
	v_mfma_f32_16x16x32_bf16 v[104:107], v[164:167], v[196:199], 0
	v_mfma_f32_16x16x32_bf16 v[92:95], v[148:151], v[204:207], 0
	v_mfma_f32_16x16x32_bf16 v[88:91], v[164:167], v[204:207], 0
	v_mfma_f32_16x16x32_bf16 v[76:79], v[148:151], v[216:219], 0
	v_mfma_f32_16x16x32_bf16 v[72:75], v[164:167], v[216:219], 0
	v_mfma_f32_16x16x32_bf16 v[124:127], v[160:163], v[192:195], v[124:127]
	v_mfma_f32_16x16x32_bf16 v[120:123], v[168:171], v[192:195], v[120:123]
	v_mfma_f32_16x16x32_bf16 v[108:111], v[160:163], v[200:203], v[108:111]
	v_mfma_f32_16x16x32_bf16 v[104:107], v[168:171], v[200:203], v[104:107]
	v_mfma_f32_16x16x32_bf16 v[92:95], v[160:163], v[208:211], v[92:95]
	v_mfma_f32_16x16x32_bf16 v[88:91], v[168:171], v[208:211], v[88:91]
	v_mfma_f32_16x16x32_bf16 v[76:79], v[160:163], v[220:223], v[76:79]
	v_mfma_f32_16x16x32_bf16 v[72:75], v[168:171], v[220:223], v[72:75]
	s_setprio 0
	s_setprio 1
	v_mfma_f32_16x16x32_bf16 v[116:119], v[172:175], v[188:191], 0
	v_mfma_f32_16x16x32_bf16 v[112:115], v[180:183], v[188:191], 0
	v_mfma_f32_16x16x32_bf16 v[100:103], v[172:175], v[196:199], 0
	v_mfma_f32_16x16x32_bf16 v[96:99], v[180:183], v[196:199], 0
	v_mfma_f32_16x16x32_bf16 v[84:87], v[172:175], v[204:207], 0
	v_mfma_f32_16x16x32_bf16 v[80:83], v[180:183], v[204:207], 0
	v_mfma_f32_16x16x32_bf16 v[68:71], v[172:175], v[216:219], 0
	v_mfma_f32_16x16x32_bf16 v[64:67], v[180:183], v[216:219], 0
	v_mfma_f32_16x16x32_bf16 v[116:119], v[176:179], v[192:195], v[116:119]
	v_mfma_f32_16x16x32_bf16 v[112:115], v[184:187], v[192:195], v[112:115]
	v_mfma_f32_16x16x32_bf16 v[100:103], v[176:179], v[200:203], v[100:103]
	v_mfma_f32_16x16x32_bf16 v[96:99], v[184:187], v[200:203], v[96:99]
	v_mfma_f32_16x16x32_bf16 v[84:87], v[176:179], v[208:211], v[84:87]
	v_mfma_f32_16x16x32_bf16 v[80:83], v[184:187], v[208:211], v[80:83]
	v_mfma_f32_16x16x32_bf16 v[68:71], v[176:179], v[220:223], v[68:71]
	v_mfma_f32_16x16x32_bf16 v[64:67], v[184:187], v[220:223], v[64:67]
	s_setprio 0
	s_barrier
	s_add_i32 s62, s49, s33
	v_lshl_add_u64 v[212:213], s[2:3], 0, v[130:131]
	s_mov_b32 m0, s62
	ds_read_b128 v[188:191], v158 offset:16384
	ds_read_b128 v[192:195], v158 offset:17408
	ds_read_b128 v[196:199], v158 offset:18432
	ds_read_b128 v[200:203], v158 offset:19456
	ds_read_b128 v[204:207], v158 offset:20480
	ds_read_b128 v[208:211], v158 offset:21504
	ds_read_b128 v[216:219], v158 offset:22528
	ds_read_b128 v[220:223], v158 offset:23552
	global_load_lds_dwordx4 v[212:213], off
	s_add_i32 m0, s62, 0x2000
	s_add_u32 s62, s2, 0x40000
	v_lshl_add_u64 v[224:225], s[2:3], 0, v[134:135]
	s_addc_u32 s63, s3, 0
	s_add_i32 s64, s50, s33
	global_load_lds_dwordx4 v[224:225], off
	v_lshl_add_u64 v[226:227], s[62:63], 0, v[130:131]
	s_mov_b32 m0, s64
	v_lshl_add_u64 v[228:229], s[36:37], 0, v[132:133]
	global_load_lds_dwordx4 v[226:227], off
	v_lshl_add_u64 v[226:227], s[62:63], 0, v[134:135]
	s_add_i32 m0, s64, 0x2000
	s_nop 0
	global_load_lds_dwordx4 v[226:227], off
	v_lshl_add_u64 v[226:227], s[36:37], 0, v[128:129]
	s_mov_b32 m0, s38
	s_nop 0
	global_load_lds_dwordx4 v[226:227], off
	s_mov_b32 m0, s39
	s_nop 0
	global_load_lds_dwordx4 v[228:229], off
	s_waitcnt vmcnt(8)
	s_waitcnt lgkmcnt(0)
	s_barrier
	s_setprio 1
	s_waitcnt lgkmcnt(0)
	v_mfma_f32_16x16x32_bf16 v[60:63], v[148:151], v[188:191], 0
	v_mfma_f32_16x16x32_bf16 v[56:59], v[164:167], v[188:191], 0
	v_mfma_f32_16x16x32_bf16 v[44:47], v[148:151], v[196:199], 0
	v_mfma_f32_16x16x32_bf16 v[40:43], v[164:167], v[196:199], 0
	v_mfma_f32_16x16x32_bf16 v[28:31], v[148:151], v[204:207], 0
	v_mfma_f32_16x16x32_bf16 v[24:27], v[164:167], v[204:207], 0
	v_mfma_f32_16x16x32_bf16 v[12:15], v[148:151], v[216:219], 0
	v_mfma_f32_16x16x32_bf16 v[8:11], v[164:167], v[216:219], 0
	v_mfma_f32_16x16x32_bf16 v[60:63], v[160:163], v[192:195], v[60:63]
	v_mfma_f32_16x16x32_bf16 v[56:59], v[168:171], v[192:195], v[56:59]
	v_mfma_f32_16x16x32_bf16 v[44:47], v[160:163], v[200:203], v[44:47]
	v_mfma_f32_16x16x32_bf16 v[40:43], v[168:171], v[200:203], v[40:43]
	v_mfma_f32_16x16x32_bf16 v[28:31], v[160:163], v[208:211], v[28:31]
	v_mfma_f32_16x16x32_bf16 v[24:27], v[168:171], v[208:211], v[24:27]
	v_mfma_f32_16x16x32_bf16 v[12:15], v[160:163], v[220:223], v[12:15]
	v_mfma_f32_16x16x32_bf16 v[8:11], v[168:171], v[220:223], v[8:11]
	s_setprio 0
	s_setprio 1
	v_mfma_f32_16x16x32_bf16 v[52:55], v[172:175], v[188:191], 0
	v_mfma_f32_16x16x32_bf16 v[48:51], v[180:183], v[188:191], 0
	v_mfma_f32_16x16x32_bf16 v[36:39], v[172:175], v[196:199], 0
	v_mfma_f32_16x16x32_bf16 v[32:35], v[180:183], v[196:199], 0
	v_mfma_f32_16x16x32_bf16 v[20:23], v[172:175], v[204:207], 0
	v_mfma_f32_16x16x32_bf16 v[16:19], v[180:183], v[204:207], 0
	v_mfma_f32_16x16x32_bf16 v[4:7], v[172:175], v[216:219], 0
	v_mfma_f32_16x16x32_bf16 v[0:3], v[180:183], v[216:219], 0
	v_mfma_f32_16x16x32_bf16 v[52:55], v[176:179], v[192:195], v[52:55]
	v_mfma_f32_16x16x32_bf16 v[48:51], v[184:187], v[192:195], v[48:51]
	v_mfma_f32_16x16x32_bf16 v[36:39], v[176:179], v[200:203], v[36:39]
	v_mfma_f32_16x16x32_bf16 v[32:35], v[184:187], v[200:203], v[32:35]
	v_mfma_f32_16x16x32_bf16 v[20:23], v[176:179], v[208:211], v[20:23]
	v_mfma_f32_16x16x32_bf16 v[16:19], v[184:187], v[208:211], v[16:19]
	v_mfma_f32_16x16x32_bf16 v[4:7], v[176:179], v[220:223], v[4:7]
	v_mfma_f32_16x16x32_bf16 v[0:3], v[184:187], v[220:223], v[0:3]
	s_setprio 0
	s_barrier
	s_branch .Lp1_peelmid

.Lp1_peelmid:
	s_add_i32 s62, 0, 0x18000
	v_add_u32_e32 v136, s62, v152
	s_add_i32 s63, 0, 0x1c000
	ds_read_b128 v[148:151], v136
	ds_read_b128 v[160:163], v136 offset:1024
	ds_read_b128 v[164:167], v136 offset:2048
	ds_read_b128 v[168:171], v136 offset:3072
	v_add_u32_e32 v136, s63, v152
	ds_read_b128 v[172:175], v136
	ds_read_b128 v[176:179], v136 offset:1024
	ds_read_b128 v[180:183], v136 offset:2048
	ds_read_b128 v[184:187], v136 offset:3072
	s_add_u32 s36, s36, 0x40000
	s_addc_u32 s37, s37, 0
	s_mov_b32 m0, s40
	v_lshl_add_u64 v[230:231], s[36:37], 0, v[128:129]
	ds_read_b128 v[188:191], v158 offset:32768
	ds_read_b128 v[192:195], v158 offset:33792
	ds_read_b128 v[196:199], v158 offset:34816
	ds_read_b128 v[200:203], v158 offset:35840
	ds_read_b128 v[204:207], v158 offset:36864
	ds_read_b128 v[208:211], v158 offset:37888
	ds_read_b128 v[216:219], v158 offset:38912
	ds_read_b128 v[220:223], v158 offset:39936
	global_load_lds_dwordx4 v[230:231], off
	v_lshl_add_u64 v[230:231], s[36:37], 0, v[132:133]
	s_mov_b32 m0, s41
	s_nop 0
	global_load_lds_dwordx4 v[230:231], off
	s_waitcnt vmcnt(8)
	s_waitcnt lgkmcnt(0)
	s_barrier
	s_setprio 1
	s_waitcnt lgkmcnt(0)
	v_mfma_f32_16x16x32_bf16 v[124:127], v[148:151], v[188:191], v[124:127]
	v_mfma_f32_16x16x32_bf16 v[120:123], v[164:167], v[188:191], v[120:123]
	v_mfma_f32_16x16x32_bf16 v[108:111], v[148:151], v[196:199], v[108:111]
	v_mfma_f32_16x16x32_bf16 v[104:107], v[164:167], v[196:199], v[104:107]
	v_mfma_f32_16x16x32_bf16 v[92:95], v[148:151], v[204:207], v[92:95]
	v_mfma_f32_16x16x32_bf16 v[88:91], v[164:167], v[204:207], v[88:91]
	v_mfma_f32_16x16x32_bf16 v[76:79], v[148:151], v[216:219], v[76:79]
	v_mfma_f32_16x16x32_bf16 v[72:75], v[164:167], v[216:219], v[72:75]
	v_mfma_f32_16x16x32_bf16 v[124:127], v[160:163], v[192:195], v[124:127]
	v_mfma_f32_16x16x32_bf16 v[120:123], v[168:171], v[192:195], v[120:123]
	v_mfma_f32_16x16x32_bf16 v[108:111], v[160:163], v[200:203], v[108:111]
	v_mfma_f32_16x16x32_bf16 v[104:107], v[168:171], v[200:203], v[104:107]
	v_mfma_f32_16x16x32_bf16 v[92:95], v[160:163], v[208:211], v[92:95]
	v_mfma_f32_16x16x32_bf16 v[88:91], v[168:171], v[208:211], v[88:91]
	v_mfma_f32_16x16x32_bf16 v[76:79], v[160:163], v[220:223], v[76:79]
	v_mfma_f32_16x16x32_bf16 v[72:75], v[168:171], v[220:223], v[72:75]
	s_setprio 0
	s_setprio 1
	v_mfma_f32_16x16x32_bf16 v[116:119], v[172:175], v[188:191], v[116:119]
	v_mfma_f32_16x16x32_bf16 v[112:115], v[180:183], v[188:191], v[112:115]
	v_mfma_f32_16x16x32_bf16 v[100:103], v[172:175], v[196:199], v[100:103]
	v_mfma_f32_16x16x32_bf16 v[96:99], v[180:183], v[196:199], v[96:99]
	v_mfma_f32_16x16x32_bf16 v[84:87], v[172:175], v[204:207], v[84:87]
	v_mfma_f32_16x16x32_bf16 v[80:83], v[180:183], v[204:207], v[80:83]
	v_mfma_f32_16x16x32_bf16 v[68:71], v[172:175], v[216:219], v[68:71]
	v_mfma_f32_16x16x32_bf16 v[64:67], v[180:183], v[216:219], v[64:67]
	v_mfma_f32_16x16x32_bf16 v[116:119], v[176:179], v[192:195], v[116:119]
	v_mfma_f32_16x16x32_bf16 v[112:115], v[184:187], v[192:195], v[112:115]
	v_mfma_f32_16x16x32_bf16 v[100:103], v[176:179], v[200:203], v[100:103]
	v_mfma_f32_16x16x32_bf16 v[96:99], v[184:187], v[200:203], v[96:99]
	v_mfma_f32_16x16x32_bf16 v[84:87], v[176:179], v[208:211], v[84:87]
	v_mfma_f32_16x16x32_bf16 v[80:83], v[184:187], v[208:211], v[80:83]
	v_mfma_f32_16x16x32_bf16 v[68:71], v[176:179], v[220:223], v[68:71]
	v_mfma_f32_16x16x32_bf16 v[64:67], v[184:187], v[220:223], v[64:67]
	s_setprio 0
	s_barrier
	s_add_i32 s36, s62, s33
	v_lshl_add_u64 v[212:213], v[212:213], 0, s[20:21]
	s_mov_b32 m0, s36
	ds_read_b128 v[188:191], v158 offset:49152
	ds_read_b128 v[192:195], v158 offset:50176
	ds_read_b128 v[196:199], v158 offset:51200
	ds_read_b128 v[200:203], v158 offset:52224
	ds_read_b128 v[204:207], v158 offset:53248
	ds_read_b128 v[208:211], v158 offset:54272
	ds_read_b128 v[216:219], v158 offset:55296
	ds_read_b128 v[220:223], v158 offset:56320
	global_load_lds_dwordx4 v[212:213], off
	s_add_i32 m0, s36, 0x2000
	s_add_u32 s2, s2, 0x40080
	v_lshl_add_u64 v[212:213], v[224:225], 0, s[20:21]
	s_addc_u32 s3, s3, 0
	s_add_i32 s36, s63, s33
	global_load_lds_dwordx4 v[212:213], off
	v_lshl_add_u64 v[212:213], s[2:3], 0, v[130:131]
	s_mov_b32 m0, s36
	s_nop 0
	global_load_lds_dwordx4 v[212:213], off
	v_lshl_add_u64 v[212:213], s[2:3], 0, v[134:135]
	s_add_i32 m0, s36, 0x2000
	s_nop 0
	global_load_lds_dwordx4 v[212:213], off
	v_lshl_add_u64 v[212:213], v[226:227], 0, s[20:21]
	s_mov_b32 m0, s43
	s_nop 0
	global_load_lds_dwordx4 v[212:213], off
	v_lshl_add_u64 v[212:213], v[228:229], 0, s[20:21]
	s_mov_b32 m0, s44
	s_nop 0
	global_load_lds_dwordx4 v[212:213], off
	s_waitcnt vmcnt(8)
	s_waitcnt lgkmcnt(0)
	s_barrier
	s_setprio 1
	s_waitcnt lgkmcnt(0)
	v_mfma_f32_16x16x32_bf16 v[60:63], v[148:151], v[188:191], v[60:63]
	v_mfma_f32_16x16x32_bf16 v[56:59], v[164:167], v[188:191], v[56:59]
	v_mfma_f32_16x16x32_bf16 v[44:47], v[148:151], v[196:199], v[44:47]
	v_mfma_f32_16x16x32_bf16 v[40:43], v[164:167], v[196:199], v[40:43]
	v_mfma_f32_16x16x32_bf16 v[28:31], v[148:151], v[204:207], v[28:31]
	v_mfma_f32_16x16x32_bf16 v[24:27], v[164:167], v[204:207], v[24:27]
	v_mfma_f32_16x16x32_bf16 v[12:15], v[148:151], v[216:219], v[12:15]
	v_mfma_f32_16x16x32_bf16 v[8:11], v[164:167], v[216:219], v[8:11]
	v_mfma_f32_16x16x32_bf16 v[60:63], v[160:163], v[192:195], v[60:63]
	v_mfma_f32_16x16x32_bf16 v[56:59], v[168:171], v[192:195], v[56:59]
	v_mfma_f32_16x16x32_bf16 v[44:47], v[160:163], v[200:203], v[44:47]
	v_mfma_f32_16x16x32_bf16 v[40:43], v[168:171], v[200:203], v[40:43]
	v_mfma_f32_16x16x32_bf16 v[28:31], v[160:163], v[208:211], v[28:31]
	v_mfma_f32_16x16x32_bf16 v[24:27], v[168:171], v[208:211], v[24:27]
	v_mfma_f32_16x16x32_bf16 v[12:15], v[160:163], v[220:223], v[12:15]
	v_mfma_f32_16x16x32_bf16 v[8:11], v[168:171], v[220:223], v[8:11]
	s_setprio 0
	s_setprio 1
	v_mfma_f32_16x16x32_bf16 v[52:55], v[172:175], v[188:191], v[52:55]
	v_mfma_f32_16x16x32_bf16 v[48:51], v[180:183], v[188:191], v[48:51]
	v_mfma_f32_16x16x32_bf16 v[36:39], v[172:175], v[196:199], v[36:39]
	v_mfma_f32_16x16x32_bf16 v[32:35], v[180:183], v[196:199], v[32:35]
	v_mfma_f32_16x16x32_bf16 v[20:23], v[172:175], v[204:207], v[20:23]
	v_mfma_f32_16x16x32_bf16 v[16:19], v[180:183], v[204:207], v[16:19]
	v_mfma_f32_16x16x32_bf16 v[4:7], v[172:175], v[216:219], v[4:7]
	v_mfma_f32_16x16x32_bf16 v[0:3], v[180:183], v[216:219], v[0:3]
	v_mfma_f32_16x16x32_bf16 v[52:55], v[176:179], v[192:195], v[52:55]
	v_mfma_f32_16x16x32_bf16 v[48:51], v[184:187], v[192:195], v[48:51]
	v_mfma_f32_16x16x32_bf16 v[36:39], v[176:179], v[200:203], v[36:39]
	v_mfma_f32_16x16x32_bf16 v[32:35], v[184:187], v[200:203], v[32:35]
	v_mfma_f32_16x16x32_bf16 v[20:23], v[176:179], v[208:211], v[20:23]
	v_mfma_f32_16x16x32_bf16 v[16:19], v[184:187], v[208:211], v[16:19]
	v_mfma_f32_16x16x32_bf16 v[4:7], v[176:179], v[220:223], v[4:7]
	v_mfma_f32_16x16x32_bf16 v[0:3], v[184:187], v[220:223], v[0:3]
	s_setprio 0
	s_barrier
	s_add_i32 s61, s61, 2
	s_add_u32 s10, s10, 0x100
	s_addc_u32 s11, s11, 0
	s_add_u32 s59, s59, 0x100
	s_addc_u32 s60, s60, 0
	s_cmp_gt_u32 s61, 13
	s_cbranch_scc0 .LBB0_215
	s_and_b64 vcc, exec, s[22:23]
	s_cbranch_vccz .LBB0_218
	s_barrier

.LBB0_811:
	s_ashr_i32 s17, s16, 31
	s_lshl_b64 s[18:19], s[16:17], 19
	v_readlane_b32 s20, v246, 30
	v_readlane_b32 s21, v246, 31
	s_add_u32 s18, s20, s18
	s_addc_u32 s19, s21, s19
	s_and_b64 s[20:21], s[6:7], exec
	s_cselect_b32 s17, s19, s23
	s_cselect_b32 s46, s18, s22
	s_ashr_i32 s15, s14, 31
	s_lshl_b64 s[20:21], s[14:15], 19
	s_add_u32 s20, s29, s20
	v_lshl_or_b32 v2, s45, 9, v175
	s_addc_u32 s21, s30, s21
	v_ashrrev_i32_e32 v3, 31, v2
	s_and_b64 s[26:27], s[6:7], exec
	v_lshl_add_u64 v[166:167], s[8:9], 0, v[2:3]
	v_mov_b32_e32 v2, v0
	v_mov_b32_e32 v3, v0
	s_cselect_b32 s15, s21, s25
	s_cselect_b32 s47, s20, s24
	s_add_u32 s48, s24, 0x100
	v_mov_b32_e32 v1, v0
	v_lshl_add_u32 v164, s2, 8, v172
	v_lshl_add_u64 v[168:169], s[22:23], 0, v[156:157]
	v_lshl_add_u64 v[170:171], s[22:23], 0, v[158:159]
	s_addc_u32 s49, s25, 0
	s_mov_b32 s50, -2
	s_mov_b64 s[24:25], 0
	v_add_u32_e32 v1, s43, v173
	ds_read_b128 v[132:135], v1
	ds_read_b128 v[136:139], v1 offset:1024
	ds_read_b128 v[140:143], v1 offset:2048
	ds_read_b128 v[144:147], v1 offset:3072
	v_add_u32_e32 v1, s44, v173
	s_add_u32 s2, s22, s24
	ds_read_b128 v[178:181], v1
	ds_read_b128 v[182:185], v1 offset:1024
	ds_read_b128 v[186:189], v1 offset:2048
	ds_read_b128 v[190:193], v1 offset:3072
	s_addc_u32 s3, s23, s25
	s_add_u32 s2, s2, 0x100
	s_addc_u32 s3, s3, 0
	s_add_u32 s51, s48, s24
	s_addc_u32 s52, s49, s25
	s_cmpk_eq_i32 s24, 0x700
	s_cselect_b32 s27, s17, s3
	s_cselect_b32 s26, s46, s2
	s_cselect_b32 s3, s15, s52
	s_cselect_b32 s2, s47, s51
	v_lshl_add_u64 v[2:3], v[168:169], 0, s[24:25]
	s_add_i32 m0, s33, 0xc000
	ds_read_b128 v[194:197], v176
	ds_read_b128 v[198:201], v176 offset:1024
	ds_read_b128 v[202:205], v176 offset:2048
	ds_read_b128 v[206:209], v176 offset:3072
	ds_read_b128 v[210:213], v176 offset:4096
	ds_read_b128 v[216:219], v176 offset:5120
	ds_read_b128 v[220:223], v176 offset:6144
	ds_read_b128 v[224:227], v176 offset:7168
	global_load_lds_dwordx4 v[2:3], off
	v_lshl_add_u64 v[2:3], v[170:171], 0, s[24:25]
	s_add_i32 m0, s33, 0xe000
	s_nop 0
	global_load_lds_dwordx4 v[2:3], off
	s_waitcnt vmcnt(8)
	s_waitcnt lgkmcnt(0)
	s_barrier
	s_setprio 1
	s_waitcnt lgkmcnt(0)
	v_mfma_f32_16x16x32_bf16 v[128:131], v[132:135], v[194:197], 0
	v_mfma_f32_16x16x32_bf16 v[124:127], v[140:143], v[194:197], 0
	v_mfma_f32_16x16x32_bf16 v[112:115], v[132:135], v[202:205], 0
	v_mfma_f32_16x16x32_bf16 v[108:111], v[140:143], v[202:205], 0
	v_mfma_f32_16x16x32_bf16 v[96:99], v[132:135], v[210:213], 0
	v_mfma_f32_16x16x32_bf16 v[92:95], v[140:143], v[210:213], 0
	v_mfma_f32_16x16x32_bf16 v[80:83], v[132:135], v[220:223], 0
	v_mfma_f32_16x16x32_bf16 v[76:79], v[140:143], v[220:223], 0
	v_mfma_f32_16x16x32_bf16 v[128:131], v[136:139], v[198:201], v[128:131]
	v_mfma_f32_16x16x32_bf16 v[124:127], v[144:147], v[198:201], v[124:127]
	v_mfma_f32_16x16x32_bf16 v[112:115], v[136:139], v[206:209], v[112:115]
	v_mfma_f32_16x16x32_bf16 v[108:111], v[144:147], v[206:209], v[108:111]
	v_mfma_f32_16x16x32_bf16 v[96:99], v[136:139], v[216:219], v[96:99]
	v_mfma_f32_16x16x32_bf16 v[92:95], v[144:147], v[216:219], v[92:95]
	v_mfma_f32_16x16x32_bf16 v[80:83], v[136:139], v[224:227], v[80:83]
	v_mfma_f32_16x16x32_bf16 v[76:79], v[144:147], v[224:227], v[76:79]
	s_setprio 0
	s_setprio 1
	v_mfma_f32_16x16x32_bf16 v[120:123], v[178:181], v[194:197], 0
	v_mfma_f32_16x16x32_bf16 v[116:119], v[186:189], v[194:197], 0
	v_mfma_f32_16x16x32_bf16 v[104:107], v[178:181], v[202:205], 0
	v_mfma_f32_16x16x32_bf16 v[100:103], v[186:189], v[202:205], 0
	v_mfma_f32_16x16x32_bf16 v[88:91], v[178:181], v[210:213], 0
	v_mfma_f32_16x16x32_bf16 v[84:87], v[186:189], v[210:213], 0
	v_mfma_f32_16x16x32_bf16 v[72:75], v[178:181], v[220:223], 0
	v_mfma_f32_16x16x32_bf16 v[68:71], v[186:189], v[220:223], 0
	v_mfma_f32_16x16x32_bf16 v[120:123], v[182:185], v[198:201], v[120:123]
	v_mfma_f32_16x16x32_bf16 v[116:119], v[190:193], v[198:201], v[116:119]
	v_mfma_f32_16x16x32_bf16 v[104:107], v[182:185], v[206:209], v[104:107]
	v_mfma_f32_16x16x32_bf16 v[100:103], v[190:193], v[206:209], v[100:103]
	v_mfma_f32_16x16x32_bf16 v[88:91], v[182:185], v[216:219], v[88:91]
	v_mfma_f32_16x16x32_bf16 v[84:87], v[190:193], v[216:219], v[84:87]
	v_mfma_f32_16x16x32_bf16 v[72:75], v[182:185], v[224:227], v[72:75]
	v_mfma_f32_16x16x32_bf16 v[68:71], v[190:193], v[224:227], v[68:71]
	s_setprio 0
	s_barrier
	s_add_i32 s51, s43, s31
	v_lshl_add_u64 v[228:229], s[2:3], 0, v[150:151]
	s_mov_b32 m0, s51
	ds_read_b128 v[194:197], v176 offset:16384
	ds_read_b128 v[198:201], v176 offset:17408
	ds_read_b128 v[202:205], v176 offset:18432
	ds_read_b128 v[206:209], v176 offset:19456
	ds_read_b128 v[210:213], v176 offset:20480
	ds_read_b128 v[216:219], v176 offset:21504
	ds_read_b128 v[220:223], v176 offset:22528
	ds_read_b128 v[224:227], v176 offset:23552
	global_load_lds_dwordx4 v[228:229], off
	s_add_i32 m0, s51, 0x2000
	s_add_u32 s52, s2, 0x40000
	v_lshl_add_u64 v[230:231], s[2:3], 0, v[154:155]
	s_addc_u32 s53, s3, 0
	s_add_i32 s51, s44, s31
	global_load_lds_dwordx4 v[230:231], off
	v_lshl_add_u64 v[2:3], s[52:53], 0, v[150:151]
	s_mov_b32 m0, s51
	v_lshl_add_u64 v[232:233], s[26:27], 0, v[148:149]
	global_load_lds_dwordx4 v[2:3], off
	v_lshl_add_u64 v[2:3], s[52:53], 0, v[154:155]
	s_add_i32 m0, s51, 0x2000
	v_lshl_add_u64 v[234:235], s[26:27], 0, v[152:153]
	global_load_lds_dwordx4 v[2:3], off
	s_mov_b32 m0, s33
	s_nop 0
	global_load_lds_dwordx4 v[232:233], off
	s_mov_b32 m0, s34
	s_nop 0
	global_load_lds_dwordx4 v[234:235], off
	s_waitcnt vmcnt(8)
	s_waitcnt lgkmcnt(0)
	s_barrier
	s_setprio 1
	s_waitcnt lgkmcnt(0)
	v_mfma_f32_16x16x32_bf16 v[64:67], v[132:135], v[194:197], 0
	v_mfma_f32_16x16x32_bf16 v[60:63], v[140:143], v[194:197], 0
	v_mfma_f32_16x16x32_bf16 v[48:51], v[132:135], v[202:205], 0
	v_mfma_f32_16x16x32_bf16 v[44:47], v[140:143], v[202:205], 0
	v_mfma_f32_16x16x32_bf16 v[32:35], v[132:135], v[210:213], 0
	v_mfma_f32_16x16x32_bf16 v[28:31], v[140:143], v[210:213], 0
	v_mfma_f32_16x16x32_bf16 v[16:19], v[132:135], v[220:223], 0
	v_mfma_f32_16x16x32_bf16 v[12:15], v[140:143], v[220:223], 0
	v_mfma_f32_16x16x32_bf16 v[64:67], v[136:139], v[198:201], v[64:67]
	v_mfma_f32_16x16x32_bf16 v[60:63], v[144:147], v[198:201], v[60:63]
	v_mfma_f32_16x16x32_bf16 v[48:51], v[136:139], v[206:209], v[48:51]
	v_mfma_f32_16x16x32_bf16 v[44:47], v[144:147], v[206:209], v[44:47]
	v_mfma_f32_16x16x32_bf16 v[32:35], v[136:139], v[216:219], v[32:35]
	v_mfma_f32_16x16x32_bf16 v[28:31], v[144:147], v[216:219], v[28:31]
	v_mfma_f32_16x16x32_bf16 v[16:19], v[136:139], v[224:227], v[16:19]
	v_mfma_f32_16x16x32_bf16 v[12:15], v[144:147], v[224:227], v[12:15]
	s_setprio 0
	s_setprio 1
	v_mfma_f32_16x16x32_bf16 v[56:59], v[178:181], v[194:197], 0
	v_mfma_f32_16x16x32_bf16 v[52:55], v[186:189], v[194:197], 0
	v_mfma_f32_16x16x32_bf16 v[40:43], v[178:181], v[202:205], 0
	v_mfma_f32_16x16x32_bf16 v[36:39], v[186:189], v[202:205], 0
	v_mfma_f32_16x16x32_bf16 v[24:27], v[178:181], v[210:213], 0
	v_mfma_f32_16x16x32_bf16 v[20:23], v[186:189], v[210:213], 0
	v_mfma_f32_16x16x32_bf16 v[8:11], v[178:181], v[220:223], 0
	v_mfma_f32_16x16x32_bf16 v[2:5], v[186:189], v[220:223], 0
	v_mfma_f32_16x16x32_bf16 v[56:59], v[182:185], v[198:201], v[56:59]
	v_mfma_f32_16x16x32_bf16 v[52:55], v[190:193], v[198:201], v[52:55]
	v_mfma_f32_16x16x32_bf16 v[40:43], v[182:185], v[206:209], v[40:43]
	v_mfma_f32_16x16x32_bf16 v[36:39], v[190:193], v[206:209], v[36:39]
	v_mfma_f32_16x16x32_bf16 v[24:27], v[182:185], v[216:219], v[24:27]
	v_mfma_f32_16x16x32_bf16 v[20:23], v[190:193], v[216:219], v[20:23]
	v_mfma_f32_16x16x32_bf16 v[8:11], v[182:185], v[224:227], v[8:11]
	v_mfma_f32_16x16x32_bf16 v[2:5], v[190:193], v[224:227], v[2:5]
	s_setprio 0
	s_barrier
	s_branch .Lp3_peelmid

.Lp3_peelmid:
	s_add_i32 s51, 0, 0x18000
	v_add_u32_e32 v1, s51, v173
	s_add_i32 s52, 0, 0x1c000
	ds_read_b128 v[132:135], v1
	ds_read_b128 v[136:139], v1 offset:1024
	ds_read_b128 v[140:143], v1 offset:2048
	ds_read_b128 v[144:147], v1 offset:3072
	v_add_u32_e32 v1, s52, v173
	ds_read_b128 v[178:181], v1
	ds_read_b128 v[182:185], v1 offset:1024
	ds_read_b128 v[186:189], v1 offset:2048
	ds_read_b128 v[190:193], v1 offset:3072
	s_add_u32 s26, s26, 0x40000
	s_addc_u32 s27, s27, 0
	s_mov_b32 m0, s35
	v_lshl_add_u64 v[6:7], s[26:27], 0, v[148:149]
	ds_read_b128 v[194:197], v176 offset:32768
	ds_read_b128 v[198:201], v176 offset:33792
	ds_read_b128 v[202:205], v176 offset:34816
	ds_read_b128 v[206:209], v176 offset:35840
	ds_read_b128 v[210:213], v176 offset:36864
	ds_read_b128 v[216:219], v176 offset:37888
	ds_read_b128 v[220:223], v176 offset:38912
	ds_read_b128 v[224:227], v176 offset:39936
	global_load_lds_dwordx4 v[6:7], off
	v_lshl_add_u64 v[6:7], s[26:27], 0, v[152:153]
	s_mov_b32 m0, s36
	s_nop 0
	global_load_lds_dwordx4 v[6:7], off
	s_waitcnt vmcnt(8)
	s_waitcnt lgkmcnt(0)
	s_barrier
	s_setprio 1
	s_waitcnt lgkmcnt(0)
	v_mfma_f32_16x16x32_bf16 v[128:131], v[132:135], v[194:197], v[128:131]
	v_mfma_f32_16x16x32_bf16 v[124:127], v[140:143], v[194:197], v[124:127]
	v_mfma_f32_16x16x32_bf16 v[112:115], v[132:135], v[202:205], v[112:115]
	v_mfma_f32_16x16x32_bf16 v[108:111], v[140:143], v[202:205], v[108:111]
	v_mfma_f32_16x16x32_bf16 v[96:99], v[132:135], v[210:213], v[96:99]
	v_mfma_f32_16x16x32_bf16 v[92:95], v[140:143], v[210:213], v[92:95]
	v_mfma_f32_16x16x32_bf16 v[80:83], v[132:135], v[220:223], v[80:83]
	v_mfma_f32_16x16x32_bf16 v[76:79], v[140:143], v[220:223], v[76:79]
	v_mfma_f32_16x16x32_bf16 v[128:131], v[136:139], v[198:201], v[128:131]
	v_mfma_f32_16x16x32_bf16 v[124:127], v[144:147], v[198:201], v[124:127]
	v_mfma_f32_16x16x32_bf16 v[112:115], v[136:139], v[206:209], v[112:115]
	v_mfma_f32_16x16x32_bf16 v[108:111], v[144:147], v[206:209], v[108:111]
	v_mfma_f32_16x16x32_bf16 v[96:99], v[136:139], v[216:219], v[96:99]
	v_mfma_f32_16x16x32_bf16 v[92:95], v[144:147], v[216:219], v[92:95]
	v_mfma_f32_16x16x32_bf16 v[80:83], v[136:139], v[224:227], v[80:83]
	v_mfma_f32_16x16x32_bf16 v[76:79], v[144:147], v[224:227], v[76:79]
	s_setprio 0
	s_setprio 1
	v_mfma_f32_16x16x32_bf16 v[120:123], v[178:181], v[194:197], v[120:123]
	v_mfma_f32_16x16x32_bf16 v[116:119], v[186:189], v[194:197], v[116:119]
	v_mfma_f32_16x16x32_bf16 v[104:107], v[178:181], v[202:205], v[104:107]
	v_mfma_f32_16x16x32_bf16 v[100:103], v[186:189], v[202:205], v[100:103]
	v_mfma_f32_16x16x32_bf16 v[88:91], v[178:181], v[210:213], v[88:91]
	v_mfma_f32_16x16x32_bf16 v[84:87], v[186:189], v[210:213], v[84:87]
	v_mfma_f32_16x16x32_bf16 v[72:75], v[178:181], v[220:223], v[72:75]
	v_mfma_f32_16x16x32_bf16 v[68:71], v[186:189], v[220:223], v[68:71]
	v_mfma_f32_16x16x32_bf16 v[120:123], v[182:185], v[198:201], v[120:123]
	v_mfma_f32_16x16x32_bf16 v[116:119], v[190:193], v[198:201], v[116:119]
	v_mfma_f32_16x16x32_bf16 v[104:107], v[182:185], v[206:209], v[104:107]
	v_mfma_f32_16x16x32_bf16 v[100:103], v[190:193], v[206:209], v[100:103]
	v_mfma_f32_16x16x32_bf16 v[88:91], v[182:185], v[216:219], v[88:91]
	v_mfma_f32_16x16x32_bf16 v[84:87], v[190:193], v[216:219], v[84:87]
	v_mfma_f32_16x16x32_bf16 v[72:75], v[182:185], v[224:227], v[72:75]
	v_mfma_f32_16x16x32_bf16 v[68:71], v[190:193], v[224:227], v[68:71]
	s_setprio 0
	s_barrier
	s_add_i32 s26, s51, s31
	v_lshl_add_u64 v[6:7], v[228:229], 0, s[10:11]
	s_mov_b32 m0, s26
	ds_read_b128 v[194:197], v176 offset:49152
	ds_read_b128 v[198:201], v176 offset:50176
	ds_read_b128 v[202:205], v176 offset:51200
	ds_read_b128 v[206:209], v176 offset:52224
	ds_read_b128 v[210:213], v176 offset:53248
	ds_read_b128 v[216:219], v176 offset:54272
	ds_read_b128 v[220:223], v176 offset:55296
	ds_read_b128 v[224:227], v176 offset:56320
	global_load_lds_dwordx4 v[6:7], off
	s_add_i32 m0, s26, 0x2000
	s_add_u32 s2, s2, 0x40080
	v_lshl_add_u64 v[6:7], v[230:231], 0, s[10:11]
	s_addc_u32 s3, s3, 0
	s_add_i32 s26, s52, s31
	global_load_lds_dwordx4 v[6:7], off
	v_lshl_add_u64 v[6:7], s[2:3], 0, v[150:151]
	s_mov_b32 m0, s26
	s_nop 0
	global_load_lds_dwordx4 v[6:7], off
	v_lshl_add_u64 v[6:7], s[2:3], 0, v[154:155]
	s_add_i32 m0, s26, 0x2000
	s_nop 0
	global_load_lds_dwordx4 v[6:7], off
	v_lshl_add_u64 v[6:7], v[232:233], 0, s[10:11]
	s_mov_b32 m0, s38
	s_nop 0
	global_load_lds_dwordx4 v[6:7], off
	v_lshl_add_u64 v[6:7], v[234:235], 0, s[10:11]
	s_mov_b32 m0, s39
	s_nop 0
	global_load_lds_dwordx4 v[6:7], off
	s_waitcnt vmcnt(8)
	s_waitcnt lgkmcnt(0)
	s_barrier
	s_setprio 1
	s_waitcnt lgkmcnt(0)
	v_mfma_f32_16x16x32_bf16 v[64:67], v[132:135], v[194:197], v[64:67]
	v_mfma_f32_16x16x32_bf16 v[60:63], v[140:143], v[194:197], v[60:63]
	v_mfma_f32_16x16x32_bf16 v[48:51], v[132:135], v[202:205], v[48:51]
	v_mfma_f32_16x16x32_bf16 v[44:47], v[140:143], v[202:205], v[44:47]
	v_mfma_f32_16x16x32_bf16 v[32:35], v[132:135], v[210:213], v[32:35]
	v_mfma_f32_16x16x32_bf16 v[28:31], v[140:143], v[210:213], v[28:31]
	v_mfma_f32_16x16x32_bf16 v[16:19], v[132:135], v[220:223], v[16:19]
	v_mfma_f32_16x16x32_bf16 v[12:15], v[140:143], v[220:223], v[12:15]
	v_mfma_f32_16x16x32_bf16 v[64:67], v[136:139], v[198:201], v[64:67]
	v_mfma_f32_16x16x32_bf16 v[60:63], v[144:147], v[198:201], v[60:63]
	v_mfma_f32_16x16x32_bf16 v[48:51], v[136:139], v[206:209], v[48:51]
	v_mfma_f32_16x16x32_bf16 v[44:47], v[144:147], v[206:209], v[44:47]
	v_mfma_f32_16x16x32_bf16 v[32:35], v[136:139], v[216:219], v[32:35]
	v_mfma_f32_16x16x32_bf16 v[28:31], v[144:147], v[216:219], v[28:31]
	v_mfma_f32_16x16x32_bf16 v[16:19], v[136:139], v[224:227], v[16:19]
	v_mfma_f32_16x16x32_bf16 v[12:15], v[144:147], v[224:227], v[12:15]
	s_setprio 0
	s_setprio 1
	v_mfma_f32_16x16x32_bf16 v[56:59], v[178:181], v[194:197], v[56:59]
	v_mfma_f32_16x16x32_bf16 v[52:55], v[186:189], v[194:197], v[52:55]
	v_mfma_f32_16x16x32_bf16 v[40:43], v[178:181], v[202:205], v[40:43]
	v_mfma_f32_16x16x32_bf16 v[36:39], v[186:189], v[202:205], v[36:39]
	v_mfma_f32_16x16x32_bf16 v[24:27], v[178:181], v[210:213], v[24:27]
	v_mfma_f32_16x16x32_bf16 v[20:23], v[186:189], v[210:213], v[20:23]
	v_mfma_f32_16x16x32_bf16 v[6:9], v[178:181], v[220:223], v[8:11]
	v_mfma_f32_16x16x32_bf16 v[2:5], v[186:189], v[220:223], v[2:5]
	v_mfma_f32_16x16x32_bf16 v[56:59], v[182:185], v[198:201], v[56:59]
	v_mfma_f32_16x16x32_bf16 v[52:55], v[190:193], v[198:201], v[52:55]
	v_mfma_f32_16x16x32_bf16 v[40:43], v[182:185], v[206:209], v[40:43]
	v_mfma_f32_16x16x32_bf16 v[36:39], v[190:193], v[206:209], v[36:39]
	v_mfma_f32_16x16x32_bf16 v[24:27], v[182:185], v[216:219], v[24:27]
	v_mfma_f32_16x16x32_bf16 v[20:23], v[190:193], v[216:219], v[20:23]
	v_mfma_f32_16x16x32_bf16 v[8:11], v[182:185], v[224:227], v[6:9]
	v_mfma_f32_16x16x32_bf16 v[4:7], v[190:193], v[224:227], v[2:5]
	s_setprio 0
	s_barrier
	s_add_i32 s50, s50, 2
	s_add_u32 s24, s24, 0x100
	s_addc_u32 s25, s25, 0
	s_cmp_gt_u32 s50, 13
	s_cbranch_scc1 .LBB0_815

.LBB0_964:
	s_ashr_i32 s17, s16, 31
	s_lshl_b64 s[18:19], s[16:17], 19
	s_add_u32 s18, s88, s18
	s_addc_u32 s19, s89, s19
	s_and_b64 s[20:21], s[10:11], exec
	s_cselect_b32 s17, s19, s27
	s_cselect_b32 s44, s18, s26
	s_ashr_i32 s15, s14, 31
	s_lshl_b64 s[20:21], s[14:15], 19
	s_add_u32 s20, s30, s20
	s_addc_u32 s21, s31, s21
	s_and_b64 s[28:29], s[10:11], exec
	s_cselect_b32 s15, s21, s3
	s_cselect_b32 s45, s20, s2
	s_add_u32 s26, s26, 0x40080
	s_addc_u32 s27, s27, 0
	s_add_u32 s46, s2, 0x100
	s_addc_u32 s47, s3, 0
	s_mov_b32 s48, -2
	s_waitcnt lgkmcnt(0)
	ds_read_b128 v[144:147], v151
	ds_read_b128 v[156:159], v151 offset:1024
	ds_read_b128 v[160:163], v151 offset:2048
	ds_read_b128 v[164:167], v151 offset:3072
	ds_read_b128 v[168:171], v152
	ds_read_b128 v[172:175], v152 offset:1024
	ds_read_b128 v[176:179], v152 offset:2048
	ds_read_b128 v[180:183], v152 offset:3072
	s_add_u32 s2, s26, 0xfffc0080
	s_addc_u32 s3, s27, -1
	s_cmp_eq_u32 s48, 12
	s_cselect_b32 s29, s17, s3
	s_cselect_b32 s28, s44, s2
	s_cselect_b32 s3, s15, s47
	s_cselect_b32 s2, s45, s46
	v_lshl_add_u64 v[212:213], s[26:27], 0, v[136:137]
	s_add_i32 m0, s23, 0xc000
	ds_read_b128 v[184:187], v153
	ds_read_b128 v[188:191], v153 offset:1024
	ds_read_b128 v[192:195], v153 offset:2048
	ds_read_b128 v[196:199], v153 offset:3072
	ds_read_b128 v[200:203], v153 offset:4096
	ds_read_b128 v[204:207], v153 offset:5120
	ds_read_b128 v[208:211], v153 offset:6144
	ds_read_b128 v[216:219], v153 offset:7168
	global_load_lds_dwordx4 v[212:213], off
	v_lshl_add_u64 v[212:213], s[26:27], 0, v[138:139]
	s_add_i32 m0, s23, 0xe000
	s_nop 0
	global_load_lds_dwordx4 v[212:213], off
	s_waitcnt vmcnt(8)
	s_waitcnt lgkmcnt(0)
	s_barrier
	s_setprio 1
	s_waitcnt lgkmcnt(0)
	v_mfma_f32_16x16x32_bf16 v[124:127], v[144:147], v[184:187], 0
	v_mfma_f32_16x16x32_bf16 v[120:123], v[160:163], v[184:187], 0
	v_mfma_f32_16x16x32_bf16 v[108:111], v[144:147], v[192:195], 0
	v_mfma_f32_16x16x32_bf16 v[104:107], v[160:163], v[192:195], 0
	v_mfma_f32_16x16x32_bf16 v[92:95], v[144:147], v[200:203], 0
	v_mfma_f32_16x16x32_bf16 v[88:91], v[160:163], v[200:203], 0
	v_mfma_f32_16x16x32_bf16 v[76:79], v[144:147], v[208:211], 0
	v_mfma_f32_16x16x32_bf16 v[72:75], v[160:163], v[208:211], 0
	v_mfma_f32_16x16x32_bf16 v[124:127], v[156:159], v[188:191], v[124:127]
	v_mfma_f32_16x16x32_bf16 v[120:123], v[164:167], v[188:191], v[120:123]
	v_mfma_f32_16x16x32_bf16 v[108:111], v[156:159], v[196:199], v[108:111]
	v_mfma_f32_16x16x32_bf16 v[104:107], v[164:167], v[196:199], v[104:107]
	v_mfma_f32_16x16x32_bf16 v[92:95], v[156:159], v[204:207], v[92:95]
	v_mfma_f32_16x16x32_bf16 v[88:91], v[164:167], v[204:207], v[88:91]
	v_mfma_f32_16x16x32_bf16 v[76:79], v[156:159], v[216:219], v[76:79]
	v_mfma_f32_16x16x32_bf16 v[72:75], v[164:167], v[216:219], v[72:75]
	s_setprio 0
	s_setprio 1
	v_mfma_f32_16x16x32_bf16 v[116:119], v[168:171], v[184:187], 0
	v_mfma_f32_16x16x32_bf16 v[112:115], v[176:179], v[184:187], 0
	v_mfma_f32_16x16x32_bf16 v[100:103], v[168:171], v[192:195], 0
	v_mfma_f32_16x16x32_bf16 v[96:99], v[176:179], v[192:195], 0
	v_mfma_f32_16x16x32_bf16 v[84:87], v[168:171], v[200:203], 0
	v_mfma_f32_16x16x32_bf16 v[80:83], v[176:179], v[200:203], 0
	v_mfma_f32_16x16x32_bf16 v[68:71], v[168:171], v[208:211], 0
	v_mfma_f32_16x16x32_bf16 v[64:67], v[176:179], v[208:211], 0
	v_mfma_f32_16x16x32_bf16 v[116:119], v[172:175], v[188:191], v[116:119]
	v_mfma_f32_16x16x32_bf16 v[112:115], v[180:183], v[188:191], v[112:115]
	v_mfma_f32_16x16x32_bf16 v[100:103], v[172:175], v[196:199], v[100:103]
	v_mfma_f32_16x16x32_bf16 v[96:99], v[180:183], v[196:199], v[96:99]
	v_mfma_f32_16x16x32_bf16 v[84:87], v[172:175], v[204:207], v[84:87]
	v_mfma_f32_16x16x32_bf16 v[80:83], v[180:183], v[204:207], v[80:83]
	v_mfma_f32_16x16x32_bf16 v[68:71], v[172:175], v[216:219], v[68:71]
	v_mfma_f32_16x16x32_bf16 v[64:67], v[180:183], v[216:219], v[64:67]
	s_setprio 0
	s_barrier
	s_add_i32 s49, s42, s33
	v_lshl_add_u64 v[212:213], s[2:3], 0, v[130:131]
	s_mov_b32 m0, s49
	ds_read_b128 v[184:187], v153 offset:16384
	ds_read_b128 v[188:191], v153 offset:17408
	ds_read_b128 v[192:195], v153 offset:18432
	ds_read_b128 v[196:199], v153 offset:19456
	ds_read_b128 v[200:203], v153 offset:20480
	ds_read_b128 v[204:207], v153 offset:21504
	ds_read_b128 v[208:211], v153 offset:22528
	ds_read_b128 v[216:219], v153 offset:23552
	global_load_lds_dwordx4 v[212:213], off
	s_add_i32 m0, s49, 0x2000
	s_add_u32 s50, s2, 0x40000
	v_lshl_add_u64 v[220:221], s[2:3], 0, v[134:135]
	s_addc_u32 s51, s3, 0
	s_add_i32 s49, s43, s33
	global_load_lds_dwordx4 v[220:221], off
	v_lshl_add_u64 v[222:223], s[50:51], 0, v[130:131]
	s_mov_b32 m0, s49
	v_lshl_add_u64 v[224:225], s[28:29], 0, v[132:133]
	global_load_lds_dwordx4 v[222:223], off
	v_lshl_add_u64 v[222:223], s[50:51], 0, v[134:135]
	s_add_i32 m0, s49, 0x2000
	s_nop 0
	global_load_lds_dwordx4 v[222:223], off
	v_lshl_add_u64 v[222:223], s[28:29], 0, v[128:129]
	s_mov_b32 m0, s23
	s_nop 0
	global_load_lds_dwordx4 v[222:223], off
	s_mov_b32 m0, s25
	s_nop 0
	global_load_lds_dwordx4 v[224:225], off
	s_waitcnt vmcnt(8)
	s_waitcnt lgkmcnt(0)
	s_barrier
	s_setprio 1
	s_waitcnt lgkmcnt(0)
	v_mfma_f32_16x16x32_bf16 v[60:63], v[144:147], v[184:187], 0
	v_mfma_f32_16x16x32_bf16 v[56:59], v[160:163], v[184:187], 0
	v_mfma_f32_16x16x32_bf16 v[44:47], v[144:147], v[192:195], 0
	v_mfma_f32_16x16x32_bf16 v[40:43], v[160:163], v[192:195], 0
	v_mfma_f32_16x16x32_bf16 v[28:31], v[144:147], v[200:203], 0
	v_mfma_f32_16x16x32_bf16 v[24:27], v[160:163], v[200:203], 0
	v_mfma_f32_16x16x32_bf16 v[12:15], v[144:147], v[208:211], 0
	v_mfma_f32_16x16x32_bf16 v[8:11], v[160:163], v[208:211], 0
	v_mfma_f32_16x16x32_bf16 v[60:63], v[156:159], v[188:191], v[60:63]
	v_mfma_f32_16x16x32_bf16 v[56:59], v[164:167], v[188:191], v[56:59]
	v_mfma_f32_16x16x32_bf16 v[44:47], v[156:159], v[196:199], v[44:47]
	v_mfma_f32_16x16x32_bf16 v[40:43], v[164:167], v[196:199], v[40:43]
	v_mfma_f32_16x16x32_bf16 v[28:31], v[156:159], v[204:207], v[28:31]
	v_mfma_f32_16x16x32_bf16 v[24:27], v[164:167], v[204:207], v[24:27]
	v_mfma_f32_16x16x32_bf16 v[12:15], v[156:159], v[216:219], v[12:15]
	v_mfma_f32_16x16x32_bf16 v[8:11], v[164:167], v[216:219], v[8:11]
	s_setprio 0
	s_setprio 1
	v_mfma_f32_16x16x32_bf16 v[52:55], v[168:171], v[184:187], 0
	v_mfma_f32_16x16x32_bf16 v[48:51], v[176:179], v[184:187], 0
	v_mfma_f32_16x16x32_bf16 v[36:39], v[168:171], v[192:195], 0
	v_mfma_f32_16x16x32_bf16 v[32:35], v[176:179], v[192:195], 0
	v_mfma_f32_16x16x32_bf16 v[20:23], v[168:171], v[200:203], 0
	v_mfma_f32_16x16x32_bf16 v[16:19], v[176:179], v[200:203], 0
	v_mfma_f32_16x16x32_bf16 v[4:7], v[168:171], v[208:211], 0
	v_mfma_f32_16x16x32_bf16 v[0:3], v[176:179], v[208:211], 0
	v_mfma_f32_16x16x32_bf16 v[52:55], v[172:175], v[188:191], v[52:55]
	v_mfma_f32_16x16x32_bf16 v[48:51], v[180:183], v[188:191], v[48:51]
	v_mfma_f32_16x16x32_bf16 v[36:39], v[172:175], v[196:199], v[36:39]
	v_mfma_f32_16x16x32_bf16 v[32:35], v[180:183], v[196:199], v[32:35]
	v_mfma_f32_16x16x32_bf16 v[20:23], v[172:175], v[204:207], v[20:23]
	v_mfma_f32_16x16x32_bf16 v[16:19], v[180:183], v[204:207], v[16:19]
	v_mfma_f32_16x16x32_bf16 v[4:7], v[172:175], v[216:219], v[4:7]
	v_mfma_f32_16x16x32_bf16 v[0:3], v[180:183], v[216:219], v[0:3]
	s_setprio 0
	s_barrier
	s_branch .Lp4_peelmid

.Lp4_peelmid:
	s_add_i32 s49, 0, 0x18000
	v_add_u32_e32 v155, s49, v149
	s_add_i32 s50, 0, 0x1c000
	ds_read_b128 v[144:147], v155
	ds_read_b128 v[156:159], v155 offset:1024
	ds_read_b128 v[160:163], v155 offset:2048
	ds_read_b128 v[164:167], v155 offset:3072
	v_add_u32_e32 v155, s50, v149
	ds_read_b128 v[168:171], v155
	ds_read_b128 v[172:175], v155 offset:1024
	ds_read_b128 v[176:179], v155 offset:2048
	ds_read_b128 v[180:183], v155 offset:3072
	s_add_u32 s28, s28, 0x40000
	s_addc_u32 s29, s29, 0
	s_mov_b32 m0, s34
	v_lshl_add_u64 v[226:227], s[28:29], 0, v[128:129]
	ds_read_b128 v[184:187], v153 offset:32768
	ds_read_b128 v[188:191], v153 offset:33792
	ds_read_b128 v[192:195], v153 offset:34816
	ds_read_b128 v[196:199], v153 offset:35840
	ds_read_b128 v[200:203], v153 offset:36864
	ds_read_b128 v[204:207], v153 offset:37888
	ds_read_b128 v[208:211], v153 offset:38912
	ds_read_b128 v[216:219], v153 offset:39936
	global_load_lds_dwordx4 v[226:227], off
	v_lshl_add_u64 v[226:227], s[28:29], 0, v[132:133]
	s_mov_b32 m0, s35
	s_nop 0
	global_load_lds_dwordx4 v[226:227], off
	s_waitcnt vmcnt(8)
	s_waitcnt lgkmcnt(0)
	s_barrier
	s_setprio 1
	s_waitcnt lgkmcnt(0)
	v_mfma_f32_16x16x32_bf16 v[124:127], v[144:147], v[184:187], v[124:127]
	v_mfma_f32_16x16x32_bf16 v[120:123], v[160:163], v[184:187], v[120:123]
	v_mfma_f32_16x16x32_bf16 v[108:111], v[144:147], v[192:195], v[108:111]
	v_mfma_f32_16x16x32_bf16 v[104:107], v[160:163], v[192:195], v[104:107]
	v_mfma_f32_16x16x32_bf16 v[92:95], v[144:147], v[200:203], v[92:95]
	v_mfma_f32_16x16x32_bf16 v[88:91], v[160:163], v[200:203], v[88:91]
	v_mfma_f32_16x16x32_bf16 v[76:79], v[144:147], v[208:211], v[76:79]
	v_mfma_f32_16x16x32_bf16 v[72:75], v[160:163], v[208:211], v[72:75]
	v_mfma_f32_16x16x32_bf16 v[124:127], v[156:159], v[188:191], v[124:127]
	v_mfma_f32_16x16x32_bf16 v[120:123], v[164:167], v[188:191], v[120:123]
	v_mfma_f32_16x16x32_bf16 v[108:111], v[156:159], v[196:199], v[108:111]
	v_mfma_f32_16x16x32_bf16 v[104:107], v[164:167], v[196:199], v[104:107]
	v_mfma_f32_16x16x32_bf16 v[92:95], v[156:159], v[204:207], v[92:95]
	v_mfma_f32_16x16x32_bf16 v[88:91], v[164:167], v[204:207], v[88:91]
	v_mfma_f32_16x16x32_bf16 v[76:79], v[156:159], v[216:219], v[76:79]
	v_mfma_f32_16x16x32_bf16 v[72:75], v[164:167], v[216:219], v[72:75]
	s_setprio 0
	s_setprio 1
	v_mfma_f32_16x16x32_bf16 v[116:119], v[168:171], v[184:187], v[116:119]
	v_mfma_f32_16x16x32_bf16 v[112:115], v[176:179], v[184:187], v[112:115]
	v_mfma_f32_16x16x32_bf16 v[100:103], v[168:171], v[192:195], v[100:103]
	v_mfma_f32_16x16x32_bf16 v[96:99], v[176:179], v[192:195], v[96:99]
	v_mfma_f32_16x16x32_bf16 v[84:87], v[168:171], v[200:203], v[84:87]
	v_mfma_f32_16x16x32_bf16 v[80:83], v[176:179], v[200:203], v[80:83]
	v_mfma_f32_16x16x32_bf16 v[68:71], v[168:171], v[208:211], v[68:71]
	v_mfma_f32_16x16x32_bf16 v[64:67], v[176:179], v[208:211], v[64:67]
	v_mfma_f32_16x16x32_bf16 v[116:119], v[172:175], v[188:191], v[116:119]
	v_mfma_f32_16x16x32_bf16 v[112:115], v[180:183], v[188:191], v[112:115]
	v_mfma_f32_16x16x32_bf16 v[100:103], v[172:175], v[196:199], v[100:103]
	v_mfma_f32_16x16x32_bf16 v[96:99], v[180:183], v[196:199], v[96:99]
	v_mfma_f32_16x16x32_bf16 v[84:87], v[172:175], v[204:207], v[84:87]
	v_mfma_f32_16x16x32_bf16 v[80:83], v[180:183], v[204:207], v[80:83]
	v_mfma_f32_16x16x32_bf16 v[68:71], v[172:175], v[216:219], v[68:71]
	v_mfma_f32_16x16x32_bf16 v[64:67], v[180:183], v[216:219], v[64:67]
	s_setprio 0
	s_barrier
	s_add_i32 s28, s49, s33
	v_lshl_add_u64 v[212:213], v[212:213], 0, s[4:5]
	s_mov_b32 m0, s28
	ds_read_b128 v[184:187], v153 offset:49152
	ds_read_b128 v[188:191], v153 offset:50176
	ds_read_b128 v[192:195], v153 offset:51200
	ds_read_b128 v[196:199], v153 offset:52224
	ds_read_b128 v[200:203], v153 offset:53248
	ds_read_b128 v[204:207], v153 offset:54272
	ds_read_b128 v[208:211], v153 offset:55296
	ds_read_b128 v[216:219], v153 offset:56320
	global_load_lds_dwordx4 v[212:213], off
	s_add_i32 m0, s28, 0x2000
	s_add_u32 s2, s2, 0x40080
	v_lshl_add_u64 v[212:213], v[220:221], 0, s[4:5]
	s_addc_u32 s3, s3, 0
	s_add_i32 s28, s50, s33
	global_load_lds_dwordx4 v[212:213], off
	v_lshl_add_u64 v[212:213], s[2:3], 0, v[130:131]
	s_mov_b32 m0, s28
	s_nop 0
	global_load_lds_dwordx4 v[212:213], off
	v_lshl_add_u64 v[212:213], s[2:3], 0, v[134:135]
	s_add_i32 m0, s28, 0x2000
	s_nop 0
	global_load_lds_dwordx4 v[212:213], off
	v_lshl_add_u64 v[212:213], v[222:223], 0, s[4:5]
	s_mov_b32 m0, s37
	s_nop 0
	global_load_lds_dwordx4 v[212:213], off
	v_lshl_add_u64 v[212:213], v[224:225], 0, s[4:5]
	s_mov_b32 m0, s38
	s_nop 0
	global_load_lds_dwordx4 v[212:213], off
	s_waitcnt vmcnt(8)
	s_waitcnt lgkmcnt(0)
	s_barrier
	s_setprio 1
	s_waitcnt lgkmcnt(0)
	v_mfma_f32_16x16x32_bf16 v[60:63], v[144:147], v[184:187], v[60:63]
	v_mfma_f32_16x16x32_bf16 v[56:59], v[160:163], v[184:187], v[56:59]
	v_mfma_f32_16x16x32_bf16 v[44:47], v[144:147], v[192:195], v[44:47]
	v_mfma_f32_16x16x32_bf16 v[40:43], v[160:163], v[192:195], v[40:43]
	v_mfma_f32_16x16x32_bf16 v[28:31], v[144:147], v[200:203], v[28:31]
	v_mfma_f32_16x16x32_bf16 v[24:27], v[160:163], v[200:203], v[24:27]
	v_mfma_f32_16x16x32_bf16 v[12:15], v[144:147], v[208:211], v[12:15]
	v_mfma_f32_16x16x32_bf16 v[8:11], v[160:163], v[208:211], v[8:11]
	v_mfma_f32_16x16x32_bf16 v[60:63], v[156:159], v[188:191], v[60:63]
	v_mfma_f32_16x16x32_bf16 v[56:59], v[164:167], v[188:191], v[56:59]
	v_mfma_f32_16x16x32_bf16 v[44:47], v[156:159], v[196:199], v[44:47]
	v_mfma_f32_16x16x32_bf16 v[40:43], v[164:167], v[196:199], v[40:43]
	v_mfma_f32_16x16x32_bf16 v[28:31], v[156:159], v[204:207], v[28:31]
	v_mfma_f32_16x16x32_bf16 v[24:27], v[164:167], v[204:207], v[24:27]
	v_mfma_f32_16x16x32_bf16 v[12:15], v[156:159], v[216:219], v[12:15]
	v_mfma_f32_16x16x32_bf16 v[8:11], v[164:167], v[216:219], v[8:11]
	s_setprio 0
	s_setprio 1
	v_mfma_f32_16x16x32_bf16 v[52:55], v[168:171], v[184:187], v[52:55]
	v_mfma_f32_16x16x32_bf16 v[48:51], v[176:179], v[184:187], v[48:51]
	v_mfma_f32_16x16x32_bf16 v[36:39], v[168:171], v[192:195], v[36:39]
	v_mfma_f32_16x16x32_bf16 v[32:35], v[176:179], v[192:195], v[32:35]
	v_mfma_f32_16x16x32_bf16 v[20:23], v[168:171], v[200:203], v[20:23]
	v_mfma_f32_16x16x32_bf16 v[16:19], v[176:179], v[200:203], v[16:19]
	v_mfma_f32_16x16x32_bf16 v[4:7], v[168:171], v[208:211], v[4:7]
	v_mfma_f32_16x16x32_bf16 v[0:3], v[176:179], v[208:211], v[0:3]
	v_mfma_f32_16x16x32_bf16 v[52:55], v[172:175], v[188:191], v[52:55]
	v_mfma_f32_16x16x32_bf16 v[48:51], v[180:183], v[188:191], v[48:51]
	v_mfma_f32_16x16x32_bf16 v[36:39], v[172:175], v[196:199], v[36:39]
	v_mfma_f32_16x16x32_bf16 v[32:35], v[180:183], v[196:199], v[32:35]
	v_mfma_f32_16x16x32_bf16 v[20:23], v[172:175], v[204:207], v[20:23]
	v_mfma_f32_16x16x32_bf16 v[16:19], v[180:183], v[204:207], v[16:19]
	v_mfma_f32_16x16x32_bf16 v[4:7], v[172:175], v[216:219], v[4:7]
	v_mfma_f32_16x16x32_bf16 v[0:3], v[180:183], v[216:219], v[0:3]
	s_setprio 0
	s_barrier
	s_add_i32 s48, s48, 2
	s_add_u32 s26, s26, 0x100
	s_addc_u32 s27, s27, 0
	s_add_u32 s46, s46, 0x100
	s_addc_u32 s47, s47, 0
	s_cmp_gt_u32 s48, 13
	s_cbranch_scc0 .LBB0_965
	s_and_b64 vcc, exec, s[12:13]
	s_cbranch_vccz .LBB0_968
	s_barrier

.LBB0_1048:
	s_ashr_i32 s17, s16, 31
	s_lshl_b64 s[18:19], s[16:17], 19
	v_readlane_b32 s20, v246, 30
	v_readlane_b32 s21, v246, 31
	s_add_u32 s18, s20, s18
	s_addc_u32 s19, s21, s19
	s_and_b64 s[20:21], s[4:5], exec
	s_cselect_b32 s17, s19, s23
	s_cselect_b32 s45, s18, s22
	s_ashr_i32 s15, s14, 31
	s_lshl_b64 s[20:21], s[14:15], 19
	s_add_u32 s20, s26, s20
	s_addc_u32 s21, s27, s21
	s_and_b64 s[24:25], s[4:5], exec
	s_cselect_b32 s15, s21, s3
	s_cselect_b32 s46, s20, s2
	s_add_u32 s22, s22, 0x40080
	s_addc_u32 s23, s23, 0
	s_add_u32 s47, s2, 0x100
	s_addc_u32 s48, s3, 0
	s_mov_b32 s49, -2
	ds_read_b128 v[144:147], v151
	ds_read_b128 v[156:159], v151 offset:1024
	ds_read_b128 v[160:163], v151 offset:2048
	ds_read_b128 v[164:167], v151 offset:3072
	ds_read_b128 v[168:171], v152
	ds_read_b128 v[172:175], v152 offset:1024
	ds_read_b128 v[176:179], v152 offset:2048
	ds_read_b128 v[180:183], v152 offset:3072
	s_add_u32 s2, s22, 0xfffc0080
	s_addc_u32 s3, s23, -1
	s_cmp_eq_u32 s49, 12
	s_cselect_b32 s25, s17, s3
	s_cselect_b32 s24, s45, s2
	s_cselect_b32 s3, s15, s48
	s_cselect_b32 s2, s46, s47
	v_lshl_add_u64 v[212:213], s[22:23], 0, v[136:137]
	s_add_i32 m0, s31, 0xc000
	ds_read_b128 v[184:187], v153
	ds_read_b128 v[188:191], v153 offset:1024
	ds_read_b128 v[192:195], v153 offset:2048
	ds_read_b128 v[196:199], v153 offset:3072
	ds_read_b128 v[200:203], v153 offset:4096
	ds_read_b128 v[204:207], v153 offset:5120
	ds_read_b128 v[208:211], v153 offset:6144
	ds_read_b128 v[216:219], v153 offset:7168
	global_load_lds_dwordx4 v[212:213], off
	v_lshl_add_u64 v[212:213], s[22:23], 0, v[138:139]
	s_add_i32 m0, s31, 0xe000
	s_nop 0
	global_load_lds_dwordx4 v[212:213], off
	s_waitcnt vmcnt(8)
	s_waitcnt lgkmcnt(0)
	s_barrier
	s_setprio 1
	s_waitcnt lgkmcnt(0)
	v_mfma_f32_16x16x32_bf16 v[116:119], v[144:147], v[184:187], 0
	v_mfma_f32_16x16x32_bf16 v[124:127], v[160:163], v[184:187], 0
	v_mfma_f32_16x16x32_bf16 v[100:103], v[144:147], v[192:195], 0
	v_mfma_f32_16x16x32_bf16 v[108:111], v[160:163], v[192:195], 0
	v_mfma_f32_16x16x32_bf16 v[84:87], v[144:147], v[200:203], 0
	v_mfma_f32_16x16x32_bf16 v[92:95], v[160:163], v[200:203], 0
	v_mfma_f32_16x16x32_bf16 v[72:75], v[144:147], v[208:211], 0
	v_mfma_f32_16x16x32_bf16 v[76:79], v[160:163], v[208:211], 0
	v_mfma_f32_16x16x32_bf16 v[116:119], v[156:159], v[188:191], v[116:119]
	v_mfma_f32_16x16x32_bf16 v[124:127], v[164:167], v[188:191], v[124:127]
	v_mfma_f32_16x16x32_bf16 v[100:103], v[156:159], v[196:199], v[100:103]
	v_mfma_f32_16x16x32_bf16 v[108:111], v[164:167], v[196:199], v[108:111]
	v_mfma_f32_16x16x32_bf16 v[84:87], v[156:159], v[204:207], v[84:87]
	v_mfma_f32_16x16x32_bf16 v[92:95], v[164:167], v[204:207], v[92:95]
	v_mfma_f32_16x16x32_bf16 v[72:75], v[156:159], v[216:219], v[72:75]
	v_mfma_f32_16x16x32_bf16 v[76:79], v[164:167], v[216:219], v[76:79]
	s_setprio 0
	s_setprio 1
	v_mfma_f32_16x16x32_bf16 v[112:115], v[168:171], v[184:187], 0
	v_mfma_f32_16x16x32_bf16 v[120:123], v[176:179], v[184:187], 0
	v_mfma_f32_16x16x32_bf16 v[96:99], v[168:171], v[192:195], 0
	v_mfma_f32_16x16x32_bf16 v[104:107], v[176:179], v[192:195], 0
	v_mfma_f32_16x16x32_bf16 v[80:83], v[168:171], v[200:203], 0
	v_mfma_f32_16x16x32_bf16 v[88:91], v[176:179], v[200:203], 0
	v_mfma_f32_16x16x32_bf16 v[64:67], v[168:171], v[208:211], 0
	v_mfma_f32_16x16x32_bf16 v[68:71], v[176:179], v[208:211], 0
	v_mfma_f32_16x16x32_bf16 v[112:115], v[172:175], v[188:191], v[112:115]
	v_mfma_f32_16x16x32_bf16 v[120:123], v[180:183], v[188:191], v[120:123]
	v_mfma_f32_16x16x32_bf16 v[96:99], v[172:175], v[196:199], v[96:99]
	v_mfma_f32_16x16x32_bf16 v[104:107], v[180:183], v[196:199], v[104:107]
	v_mfma_f32_16x16x32_bf16 v[80:83], v[172:175], v[204:207], v[80:83]
	v_mfma_f32_16x16x32_bf16 v[88:91], v[180:183], v[204:207], v[88:91]
	v_mfma_f32_16x16x32_bf16 v[64:67], v[172:175], v[216:219], v[64:67]
	v_mfma_f32_16x16x32_bf16 v[68:71], v[180:183], v[216:219], v[68:71]
	s_setprio 0
	s_barrier
	s_add_i32 s50, s41, s28
	v_lshl_add_u64 v[212:213], s[2:3], 0, v[132:133]
	s_mov_b32 m0, s50
	ds_read_b128 v[184:187], v153 offset:16384
	ds_read_b128 v[188:191], v153 offset:17408
	ds_read_b128 v[192:195], v153 offset:18432
	ds_read_b128 v[196:199], v153 offset:19456
	ds_read_b128 v[200:203], v153 offset:20480
	ds_read_b128 v[204:207], v153 offset:21504
	ds_read_b128 v[208:211], v153 offset:22528
	ds_read_b128 v[216:219], v153 offset:23552
	global_load_lds_dwordx4 v[212:213], off
	s_add_i32 m0, s50, 0x2000
	s_add_u32 s50, s2, 0x40000
	v_lshl_add_u64 v[220:221], s[2:3], 0, v[128:129]
	s_addc_u32 s51, s3, 0
	s_add_i32 s52, s42, s28
	global_load_lds_dwordx4 v[220:221], off
	v_lshl_add_u64 v[222:223], s[50:51], 0, v[132:133]
	s_mov_b32 m0, s52
	v_lshl_add_u64 v[224:225], s[24:25], 0, v[130:131]
	global_load_lds_dwordx4 v[222:223], off
	v_lshl_add_u64 v[222:223], s[50:51], 0, v[128:129]
	s_add_i32 m0, s52, 0x2000
	s_nop 0
	global_load_lds_dwordx4 v[222:223], off
	v_lshl_add_u64 v[222:223], s[24:25], 0, v[134:135]
	s_mov_b32 m0, s31
	s_nop 0
	global_load_lds_dwordx4 v[222:223], off
	s_mov_b32 m0, s33
	s_nop 0
	global_load_lds_dwordx4 v[224:225], off
	s_waitcnt vmcnt(8)
	s_waitcnt lgkmcnt(0)
	s_barrier
	s_setprio 1
	s_waitcnt lgkmcnt(0)
	v_mfma_f32_16x16x32_bf16 v[56:59], v[144:147], v[184:187], 0
	v_mfma_f32_16x16x32_bf16 v[60:63], v[160:163], v[184:187], 0
	v_mfma_f32_16x16x32_bf16 v[40:43], v[144:147], v[192:195], 0
	v_mfma_f32_16x16x32_bf16 v[44:47], v[160:163], v[192:195], 0
	v_mfma_f32_16x16x32_bf16 v[24:27], v[144:147], v[200:203], 0
	v_mfma_f32_16x16x32_bf16 v[28:31], v[160:163], v[200:203], 0
	v_mfma_f32_16x16x32_bf16 v[8:11], v[144:147], v[208:211], 0
	v_mfma_f32_16x16x32_bf16 v[12:15], v[160:163], v[208:211], 0
	v_mfma_f32_16x16x32_bf16 v[56:59], v[156:159], v[188:191], v[56:59]
	v_mfma_f32_16x16x32_bf16 v[60:63], v[164:167], v[188:191], v[60:63]
	v_mfma_f32_16x16x32_bf16 v[40:43], v[156:159], v[196:199], v[40:43]
	v_mfma_f32_16x16x32_bf16 v[44:47], v[164:167], v[196:199], v[44:47]
	v_mfma_f32_16x16x32_bf16 v[24:27], v[156:159], v[204:207], v[24:27]
	v_mfma_f32_16x16x32_bf16 v[28:31], v[164:167], v[204:207], v[28:31]
	v_mfma_f32_16x16x32_bf16 v[8:11], v[156:159], v[216:219], v[8:11]
	v_mfma_f32_16x16x32_bf16 v[12:15], v[164:167], v[216:219], v[12:15]
	s_setprio 0
	s_setprio 1
	v_mfma_f32_16x16x32_bf16 v[48:51], v[168:171], v[184:187], 0
	v_mfma_f32_16x16x32_bf16 v[52:55], v[176:179], v[184:187], 0
	v_mfma_f32_16x16x32_bf16 v[32:35], v[168:171], v[192:195], 0
	v_mfma_f32_16x16x32_bf16 v[36:39], v[176:179], v[192:195], 0
	v_mfma_f32_16x16x32_bf16 v[16:19], v[168:171], v[200:203], 0
	v_mfma_f32_16x16x32_bf16 v[20:23], v[176:179], v[200:203], 0
	v_mfma_f32_16x16x32_bf16 v[0:3], v[168:171], v[208:211], 0
	v_mfma_f32_16x16x32_bf16 v[4:7], v[176:179], v[208:211], 0
	v_mfma_f32_16x16x32_bf16 v[48:51], v[172:175], v[188:191], v[48:51]
	v_mfma_f32_16x16x32_bf16 v[52:55], v[180:183], v[188:191], v[52:55]
	v_mfma_f32_16x16x32_bf16 v[32:35], v[172:175], v[196:199], v[32:35]
	v_mfma_f32_16x16x32_bf16 v[36:39], v[180:183], v[196:199], v[36:39]
	v_mfma_f32_16x16x32_bf16 v[16:19], v[172:175], v[204:207], v[16:19]
	v_mfma_f32_16x16x32_bf16 v[20:23], v[180:183], v[204:207], v[20:23]
	v_mfma_f32_16x16x32_bf16 v[0:3], v[172:175], v[216:219], v[0:3]
	v_mfma_f32_16x16x32_bf16 v[4:7], v[180:183], v[216:219], v[4:7]
	s_setprio 0
	s_barrier
	s_branch .Lp5_peelmid

.Lp5_peelmid:
	s_add_i32 s50, 0, 0x18000
	v_add_u32_e32 v155, s50, v149
	s_add_i32 s51, 0, 0x1c000
	ds_read_b128 v[144:147], v155
	ds_read_b128 v[156:159], v155 offset:1024
	ds_read_b128 v[160:163], v155 offset:2048
	ds_read_b128 v[164:167], v155 offset:3072
	v_add_u32_e32 v155, s51, v149
	ds_read_b128 v[168:171], v155
	ds_read_b128 v[172:175], v155 offset:1024
	ds_read_b128 v[176:179], v155 offset:2048
	ds_read_b128 v[180:183], v155 offset:3072
	s_add_u32 s24, s24, 0x40000
	s_addc_u32 s25, s25, 0
	s_mov_b32 m0, s34
	v_lshl_add_u64 v[226:227], s[24:25], 0, v[134:135]
	ds_read_b128 v[184:187], v153 offset:32768
	ds_read_b128 v[188:191], v153 offset:33792
	ds_read_b128 v[192:195], v153 offset:34816
	ds_read_b128 v[196:199], v153 offset:35840
	ds_read_b128 v[200:203], v153 offset:36864
	ds_read_b128 v[204:207], v153 offset:37888
	ds_read_b128 v[208:211], v153 offset:38912
	ds_read_b128 v[216:219], v153 offset:39936
	global_load_lds_dwordx4 v[226:227], off
	v_lshl_add_u64 v[226:227], s[24:25], 0, v[130:131]
	s_mov_b32 m0, s35
	s_nop 0
	global_load_lds_dwordx4 v[226:227], off
	s_waitcnt vmcnt(8)
	s_waitcnt lgkmcnt(0)
	s_barrier
	s_setprio 1
	s_waitcnt lgkmcnt(0)
	v_mfma_f32_16x16x32_bf16 v[116:119], v[144:147], v[184:187], v[116:119]
	v_mfma_f32_16x16x32_bf16 v[124:127], v[160:163], v[184:187], v[124:127]
	v_mfma_f32_16x16x32_bf16 v[100:103], v[144:147], v[192:195], v[100:103]
	v_mfma_f32_16x16x32_bf16 v[108:111], v[160:163], v[192:195], v[108:111]
	v_mfma_f32_16x16x32_bf16 v[84:87], v[144:147], v[200:203], v[84:87]
	v_mfma_f32_16x16x32_bf16 v[92:95], v[160:163], v[200:203], v[92:95]
	v_mfma_f32_16x16x32_bf16 v[72:75], v[144:147], v[208:211], v[72:75]
	v_mfma_f32_16x16x32_bf16 v[76:79], v[160:163], v[208:211], v[76:79]
	v_mfma_f32_16x16x32_bf16 v[116:119], v[156:159], v[188:191], v[116:119]
	v_mfma_f32_16x16x32_bf16 v[124:127], v[164:167], v[188:191], v[124:127]
	v_mfma_f32_16x16x32_bf16 v[100:103], v[156:159], v[196:199], v[100:103]
	v_mfma_f32_16x16x32_bf16 v[108:111], v[164:167], v[196:199], v[108:111]
	v_mfma_f32_16x16x32_bf16 v[84:87], v[156:159], v[204:207], v[84:87]
	v_mfma_f32_16x16x32_bf16 v[92:95], v[164:167], v[204:207], v[92:95]
	v_mfma_f32_16x16x32_bf16 v[72:75], v[156:159], v[216:219], v[72:75]
	v_mfma_f32_16x16x32_bf16 v[76:79], v[164:167], v[216:219], v[76:79]
	s_setprio 0
	s_setprio 1
	v_mfma_f32_16x16x32_bf16 v[112:115], v[168:171], v[184:187], v[112:115]
	v_mfma_f32_16x16x32_bf16 v[120:123], v[176:179], v[184:187], v[120:123]
	v_mfma_f32_16x16x32_bf16 v[96:99], v[168:171], v[192:195], v[96:99]
	v_mfma_f32_16x16x32_bf16 v[104:107], v[176:179], v[192:195], v[104:107]
	v_mfma_f32_16x16x32_bf16 v[80:83], v[168:171], v[200:203], v[80:83]
	v_mfma_f32_16x16x32_bf16 v[88:91], v[176:179], v[200:203], v[88:91]
	v_mfma_f32_16x16x32_bf16 v[64:67], v[168:171], v[208:211], v[64:67]
	v_mfma_f32_16x16x32_bf16 v[68:71], v[176:179], v[208:211], v[68:71]
	v_mfma_f32_16x16x32_bf16 v[112:115], v[172:175], v[188:191], v[112:115]
	v_mfma_f32_16x16x32_bf16 v[120:123], v[180:183], v[188:191], v[120:123]
	v_mfma_f32_16x16x32_bf16 v[96:99], v[172:175], v[196:199], v[96:99]
	v_mfma_f32_16x16x32_bf16 v[104:107], v[180:183], v[196:199], v[104:107]
	v_mfma_f32_16x16x32_bf16 v[80:83], v[172:175], v[204:207], v[80:83]
	v_mfma_f32_16x16x32_bf16 v[88:91], v[180:183], v[204:207], v[88:91]
	v_mfma_f32_16x16x32_bf16 v[64:67], v[172:175], v[216:219], v[64:67]
	v_mfma_f32_16x16x32_bf16 v[68:71], v[180:183], v[216:219], v[68:71]
	s_setprio 0
	s_barrier
	s_add_i32 s24, s50, s28
	v_lshl_add_u64 v[212:213], v[212:213], 0, s[10:11]
	s_mov_b32 m0, s24
	ds_read_b128 v[184:187], v153 offset:49152
	ds_read_b128 v[188:191], v153 offset:50176
	ds_read_b128 v[192:195], v153 offset:51200
	ds_read_b128 v[196:199], v153 offset:52224
	ds_read_b128 v[200:203], v153 offset:53248
	ds_read_b128 v[204:207], v153 offset:54272
	ds_read_b128 v[208:211], v153 offset:55296
	ds_read_b128 v[216:219], v153 offset:56320
	global_load_lds_dwordx4 v[212:213], off
	s_add_i32 m0, s24, 0x2000
	s_add_u32 s2, s2, 0x40080
	v_lshl_add_u64 v[212:213], v[220:221], 0, s[10:11]
	s_addc_u32 s3, s3, 0
	s_add_i32 s24, s51, s28
	global_load_lds_dwordx4 v[212:213], off
	v_lshl_add_u64 v[212:213], s[2:3], 0, v[132:133]
	s_mov_b32 m0, s24
	s_nop 0
	global_load_lds_dwordx4 v[212:213], off
	v_lshl_add_u64 v[212:213], s[2:3], 0, v[128:129]
	s_add_i32 m0, s24, 0x2000
	s_nop 0
	global_load_lds_dwordx4 v[212:213], off
	v_lshl_add_u64 v[212:213], v[222:223], 0, s[10:11]
	s_mov_b32 m0, s37
	s_nop 0
	global_load_lds_dwordx4 v[212:213], off
	v_lshl_add_u64 v[212:213], v[224:225], 0, s[10:11]
	s_mov_b32 m0, s38
	s_nop 0
	global_load_lds_dwordx4 v[212:213], off
	s_waitcnt vmcnt(8)
	s_waitcnt lgkmcnt(0)
	s_barrier
	s_setprio 1
	s_waitcnt lgkmcnt(0)
	v_mfma_f32_16x16x32_bf16 v[56:59], v[144:147], v[184:187], v[56:59]
	v_mfma_f32_16x16x32_bf16 v[60:63], v[160:163], v[184:187], v[60:63]
	v_mfma_f32_16x16x32_bf16 v[40:43], v[144:147], v[192:195], v[40:43]
	v_mfma_f32_16x16x32_bf16 v[44:47], v[160:163], v[192:195], v[44:47]
	v_mfma_f32_16x16x32_bf16 v[24:27], v[144:147], v[200:203], v[24:27]
	v_mfma_f32_16x16x32_bf16 v[28:31], v[160:163], v[200:203], v[28:31]
	v_mfma_f32_16x16x32_bf16 v[8:11], v[144:147], v[208:211], v[8:11]
	v_mfma_f32_16x16x32_bf16 v[12:15], v[160:163], v[208:211], v[12:15]
	v_mfma_f32_16x16x32_bf16 v[56:59], v[156:159], v[188:191], v[56:59]
	v_mfma_f32_16x16x32_bf16 v[60:63], v[164:167], v[188:191], v[60:63]
	v_mfma_f32_16x16x32_bf16 v[40:43], v[156:159], v[196:199], v[40:43]
	v_mfma_f32_16x16x32_bf16 v[44:47], v[164:167], v[196:199], v[44:47]
	v_mfma_f32_16x16x32_bf16 v[24:27], v[156:159], v[204:207], v[24:27]
	v_mfma_f32_16x16x32_bf16 v[28:31], v[164:167], v[204:207], v[28:31]
	v_mfma_f32_16x16x32_bf16 v[8:11], v[156:159], v[216:219], v[8:11]
	v_mfma_f32_16x16x32_bf16 v[12:15], v[164:167], v[216:219], v[12:15]
	s_setprio 0
	s_setprio 1
	v_mfma_f32_16x16x32_bf16 v[48:51], v[168:171], v[184:187], v[48:51]
	v_mfma_f32_16x16x32_bf16 v[52:55], v[176:179], v[184:187], v[52:55]
	v_mfma_f32_16x16x32_bf16 v[32:35], v[168:171], v[192:195], v[32:35]
	v_mfma_f32_16x16x32_bf16 v[36:39], v[176:179], v[192:195], v[36:39]
	v_mfma_f32_16x16x32_bf16 v[16:19], v[168:171], v[200:203], v[16:19]
	v_mfma_f32_16x16x32_bf16 v[20:23], v[176:179], v[200:203], v[20:23]
	v_mfma_f32_16x16x32_bf16 v[0:3], v[168:171], v[208:211], v[0:3]
	v_mfma_f32_16x16x32_bf16 v[4:7], v[176:179], v[208:211], v[4:7]
	v_mfma_f32_16x16x32_bf16 v[48:51], v[172:175], v[188:191], v[48:51]
	v_mfma_f32_16x16x32_bf16 v[52:55], v[180:183], v[188:191], v[52:55]
	v_mfma_f32_16x16x32_bf16 v[32:35], v[172:175], v[196:199], v[32:35]
	v_mfma_f32_16x16x32_bf16 v[36:39], v[180:183], v[196:199], v[36:39]
	v_mfma_f32_16x16x32_bf16 v[16:19], v[172:175], v[204:207], v[16:19]
	v_mfma_f32_16x16x32_bf16 v[20:23], v[180:183], v[204:207], v[20:23]
	v_mfma_f32_16x16x32_bf16 v[0:3], v[172:175], v[216:219], v[0:3]
	v_mfma_f32_16x16x32_bf16 v[4:7], v[180:183], v[216:219], v[4:7]
	s_setprio 0
	s_barrier
	s_add_i32 s49, s49, 2
	s_add_u32 s22, s22, 0x100
	s_addc_u32 s23, s23, 0
	s_add_u32 s47, s47, 0x100
	s_addc_u32 s48, s48, 0
	s_cmp_gt_u32 s49, 13
	s_cbranch_scc0 .LBB0_1049
	s_and_b64 vcc, exec, s[12:13]
	s_cbranch_vccz .LBB0_1052
	s_barrier

.LBB0_1128:
	s_add_u32 s56, s30, 0x100
	s_addc_u32 s57, s31, 0
	s_mov_b32 s58, -2
	ds_read_b128 v[144:147], v153
	ds_read_b128 v[156:159], v153 offset:1024
	ds_read_b128 v[160:163], v153 offset:2048
	ds_read_b128 v[164:167], v153 offset:3072
	ds_read_b128 v[168:171], v154
	ds_read_b128 v[172:175], v154 offset:1024
	ds_read_b128 v[176:179], v154 offset:2048
	ds_read_b128 v[180:183], v154 offset:3072
	s_add_u32 s30, s2, 0x100
	s_addc_u32 s31, s3, 0
	s_cmp_eq_u32 s58, 40
	s_cselect_b32 s37, s7, s31
	s_cselect_b32 s36, s6, s30
	s_cselect_b32 s35, s29, s57
	s_cselect_b32 s34, s28, s56
	v_lshl_add_u64 v[148:149], s[2:3], 0, v[136:137]
	s_add_i32 m0, s41, 0xc000
	ds_read_b128 v[184:187], v155
	ds_read_b128 v[188:191], v155 offset:1024
	ds_read_b128 v[192:195], v155 offset:2048
	ds_read_b128 v[196:199], v155 offset:3072
	ds_read_b128 v[200:203], v155 offset:4096
	ds_read_b128 v[204:207], v155 offset:5120
	ds_read_b128 v[208:211], v155 offset:6144
	ds_read_b128 v[216:219], v155 offset:7168
	global_load_lds_dwordx4 v[148:149], off
	v_lshl_add_u64 v[148:149], s[2:3], 0, v[138:139]
	s_add_i32 m0, s41, 0xe000
	s_nop 0
	global_load_lds_dwordx4 v[148:149], off
	s_waitcnt vmcnt(8)
	s_waitcnt lgkmcnt(0)
	s_barrier
	s_setprio 1
	s_waitcnt lgkmcnt(0)
	v_mfma_f32_16x16x32_bf16 v[124:127], v[144:147], v[184:187], 0
	v_mfma_f32_16x16x32_bf16 v[120:123], v[160:163], v[184:187], 0
	v_mfma_f32_16x16x32_bf16 v[108:111], v[144:147], v[192:195], 0
	v_mfma_f32_16x16x32_bf16 v[104:107], v[160:163], v[192:195], 0
	v_mfma_f32_16x16x32_bf16 v[92:95], v[144:147], v[200:203], 0
	v_mfma_f32_16x16x32_bf16 v[88:91], v[160:163], v[200:203], 0
	v_mfma_f32_16x16x32_bf16 v[76:79], v[144:147], v[208:211], 0
	v_mfma_f32_16x16x32_bf16 v[72:75], v[160:163], v[208:211], 0
	v_mfma_f32_16x16x32_bf16 v[124:127], v[156:159], v[188:191], v[124:127]
	v_mfma_f32_16x16x32_bf16 v[120:123], v[164:167], v[188:191], v[120:123]
	v_mfma_f32_16x16x32_bf16 v[108:111], v[156:159], v[196:199], v[108:111]
	v_mfma_f32_16x16x32_bf16 v[104:107], v[164:167], v[196:199], v[104:107]
	v_mfma_f32_16x16x32_bf16 v[92:95], v[156:159], v[204:207], v[92:95]
	v_mfma_f32_16x16x32_bf16 v[88:91], v[164:167], v[204:207], v[88:91]
	v_mfma_f32_16x16x32_bf16 v[76:79], v[156:159], v[216:219], v[76:79]
	v_mfma_f32_16x16x32_bf16 v[72:75], v[164:167], v[216:219], v[72:75]
	s_setprio 0
	s_setprio 1
	v_mfma_f32_16x16x32_bf16 v[116:119], v[168:171], v[184:187], 0
	v_mfma_f32_16x16x32_bf16 v[112:115], v[176:179], v[184:187], 0
	v_mfma_f32_16x16x32_bf16 v[100:103], v[168:171], v[192:195], 0
	v_mfma_f32_16x16x32_bf16 v[96:99], v[176:179], v[192:195], 0
	v_mfma_f32_16x16x32_bf16 v[84:87], v[168:171], v[200:203], 0
	v_mfma_f32_16x16x32_bf16 v[80:83], v[176:179], v[200:203], 0
	v_mfma_f32_16x16x32_bf16 v[68:71], v[168:171], v[208:211], 0
	v_mfma_f32_16x16x32_bf16 v[64:67], v[176:179], v[208:211], 0
	v_mfma_f32_16x16x32_bf16 v[116:119], v[172:175], v[188:191], v[116:119]
	v_mfma_f32_16x16x32_bf16 v[112:115], v[180:183], v[188:191], v[112:115]
	v_mfma_f32_16x16x32_bf16 v[100:103], v[172:175], v[196:199], v[100:103]
	v_mfma_f32_16x16x32_bf16 v[96:99], v[180:183], v[196:199], v[96:99]
	v_mfma_f32_16x16x32_bf16 v[84:87], v[172:175], v[204:207], v[84:87]
	v_mfma_f32_16x16x32_bf16 v[80:83], v[180:183], v[204:207], v[80:83]
	v_mfma_f32_16x16x32_bf16 v[68:71], v[172:175], v[216:219], v[68:71]
	v_mfma_f32_16x16x32_bf16 v[64:67], v[180:183], v[216:219], v[64:67]
	s_setprio 0
	s_barrier
	s_add_i32 s2, s50, s40
	v_lshl_add_u64 v[148:149], s[34:35], 0, v[130:131]
	s_mov_b32 m0, s2
	ds_read_b128 v[184:187], v155 offset:16384
	ds_read_b128 v[188:191], v155 offset:17408
	ds_read_b128 v[192:195], v155 offset:18432
	ds_read_b128 v[196:199], v155 offset:19456
	ds_read_b128 v[200:203], v155 offset:20480
	ds_read_b128 v[204:207], v155 offset:21504
	ds_read_b128 v[208:211], v155 offset:22528
	ds_read_b128 v[216:219], v155 offset:23552
	global_load_lds_dwordx4 v[148:149], off
	s_add_i32 m0, s2, 0x2000
	s_add_u32 s2, s34, 0xb0000
	v_lshl_add_u64 v[212:213], s[34:35], 0, v[134:135]
	s_addc_u32 s3, s35, 0
	s_add_i32 s59, s51, s40
	global_load_lds_dwordx4 v[212:213], off
	v_lshl_add_u64 v[220:221], s[2:3], 0, v[130:131]
	s_mov_b32 m0, s59
	v_lshl_add_u64 v[222:223], s[36:37], 0, v[132:133]
	global_load_lds_dwordx4 v[220:221], off
	v_lshl_add_u64 v[220:221], s[2:3], 0, v[134:135]
	s_add_i32 m0, s59, 0x2000
	s_nop 0
	global_load_lds_dwordx4 v[220:221], off
	v_lshl_add_u64 v[220:221], s[36:37], 0, v[128:129]
	s_mov_b32 m0, s41
	s_nop 0
	global_load_lds_dwordx4 v[220:221], off
	s_mov_b32 m0, s42
	s_nop 0
	global_load_lds_dwordx4 v[222:223], off
	s_waitcnt vmcnt(8)
	s_waitcnt lgkmcnt(0)
	s_barrier
	s_setprio 1
	s_waitcnt lgkmcnt(0)
	v_mfma_f32_16x16x32_bf16 v[60:63], v[144:147], v[184:187], 0
	v_mfma_f32_16x16x32_bf16 v[56:59], v[160:163], v[184:187], 0
	v_mfma_f32_16x16x32_bf16 v[44:47], v[144:147], v[192:195], 0
	v_mfma_f32_16x16x32_bf16 v[40:43], v[160:163], v[192:195], 0
	v_mfma_f32_16x16x32_bf16 v[28:31], v[144:147], v[200:203], 0
	v_mfma_f32_16x16x32_bf16 v[24:27], v[160:163], v[200:203], 0
	v_mfma_f32_16x16x32_bf16 v[12:15], v[144:147], v[208:211], 0
	v_mfma_f32_16x16x32_bf16 v[8:11], v[160:163], v[208:211], 0
	v_mfma_f32_16x16x32_bf16 v[60:63], v[156:159], v[188:191], v[60:63]
	v_mfma_f32_16x16x32_bf16 v[56:59], v[164:167], v[188:191], v[56:59]
	v_mfma_f32_16x16x32_bf16 v[44:47], v[156:159], v[196:199], v[44:47]
	v_mfma_f32_16x16x32_bf16 v[40:43], v[164:167], v[196:199], v[40:43]
	v_mfma_f32_16x16x32_bf16 v[28:31], v[156:159], v[204:207], v[28:31]
	v_mfma_f32_16x16x32_bf16 v[24:27], v[164:167], v[204:207], v[24:27]
	v_mfma_f32_16x16x32_bf16 v[12:15], v[156:159], v[216:219], v[12:15]
	v_mfma_f32_16x16x32_bf16 v[8:11], v[164:167], v[216:219], v[8:11]
	s_setprio 0
	s_setprio 1
	v_mfma_f32_16x16x32_bf16 v[52:55], v[168:171], v[184:187], 0
	v_mfma_f32_16x16x32_bf16 v[48:51], v[176:179], v[184:187], 0
	v_mfma_f32_16x16x32_bf16 v[36:39], v[168:171], v[192:195], 0
	v_mfma_f32_16x16x32_bf16 v[32:35], v[176:179], v[192:195], 0
	v_mfma_f32_16x16x32_bf16 v[20:23], v[168:171], v[200:203], 0
	v_mfma_f32_16x16x32_bf16 v[16:19], v[176:179], v[200:203], 0
	v_mfma_f32_16x16x32_bf16 v[4:7], v[168:171], v[208:211], 0
	v_mfma_f32_16x16x32_bf16 v[0:3], v[176:179], v[208:211], 0
	v_mfma_f32_16x16x32_bf16 v[52:55], v[172:175], v[188:191], v[52:55]
	v_mfma_f32_16x16x32_bf16 v[48:51], v[180:183], v[188:191], v[48:51]
	v_mfma_f32_16x16x32_bf16 v[36:39], v[172:175], v[196:199], v[36:39]
	v_mfma_f32_16x16x32_bf16 v[32:35], v[180:183], v[196:199], v[32:35]
	v_mfma_f32_16x16x32_bf16 v[20:23], v[172:175], v[204:207], v[20:23]
	v_mfma_f32_16x16x32_bf16 v[16:19], v[180:183], v[204:207], v[16:19]
	v_mfma_f32_16x16x32_bf16 v[4:7], v[172:175], v[216:219], v[4:7]
	v_mfma_f32_16x16x32_bf16 v[0:3], v[180:183], v[216:219], v[0:3]
	s_setprio 0
	s_barrier
	s_branch .Lp6_peelmid

.Lp6_peelmid:
	s_add_i32 s59, 0, 0x18000
	s_add_i32 s60, 0, 0x1c000
	v_add_u32_e32 v164, s59, v151
	v_add_u32_e32 v180, s60, v151
	ds_read_b128 v[144:147], v164
	ds_read_b128 v[156:159], v164 offset:1024
	ds_read_b128 v[160:163], v164 offset:2048
	ds_read_b128 v[164:167], v164 offset:3072
	ds_read_b128 v[168:171], v180
	ds_read_b128 v[172:175], v180 offset:1024
	ds_read_b128 v[176:179], v180 offset:2048
	ds_read_b128 v[180:183], v180 offset:3072
	s_add_u32 s2, s36, 0xb0000
	s_addc_u32 s3, s37, 0
	s_mov_b32 m0, s43
	v_lshl_add_u64 v[224:225], s[2:3], 0, v[128:129]
	ds_read_b128 v[184:187], v155 offset:32768
	ds_read_b128 v[188:191], v155 offset:33792
	ds_read_b128 v[192:195], v155 offset:34816
	ds_read_b128 v[196:199], v155 offset:35840
	ds_read_b128 v[200:203], v155 offset:36864
	ds_read_b128 v[204:207], v155 offset:37888
	ds_read_b128 v[208:211], v155 offset:38912
	ds_read_b128 v[216:219], v155 offset:39936
	global_load_lds_dwordx4 v[224:225], off
	v_lshl_add_u64 v[224:225], s[2:3], 0, v[132:133]
	s_mov_b32 m0, s44
	s_nop 0
	global_load_lds_dwordx4 v[224:225], off
	s_waitcnt vmcnt(8)
	s_waitcnt lgkmcnt(0)
	s_barrier
	s_setprio 1
	s_waitcnt lgkmcnt(0)
	v_mfma_f32_16x16x32_bf16 v[124:127], v[144:147], v[184:187], v[124:127]
	v_mfma_f32_16x16x32_bf16 v[120:123], v[160:163], v[184:187], v[120:123]
	v_mfma_f32_16x16x32_bf16 v[108:111], v[144:147], v[192:195], v[108:111]
	v_mfma_f32_16x16x32_bf16 v[104:107], v[160:163], v[192:195], v[104:107]
	v_mfma_f32_16x16x32_bf16 v[92:95], v[144:147], v[200:203], v[92:95]
	v_mfma_f32_16x16x32_bf16 v[88:91], v[160:163], v[200:203], v[88:91]
	v_mfma_f32_16x16x32_bf16 v[76:79], v[144:147], v[208:211], v[76:79]
	v_mfma_f32_16x16x32_bf16 v[72:75], v[160:163], v[208:211], v[72:75]
	v_mfma_f32_16x16x32_bf16 v[124:127], v[156:159], v[188:191], v[124:127]
	v_mfma_f32_16x16x32_bf16 v[120:123], v[164:167], v[188:191], v[120:123]
	v_mfma_f32_16x16x32_bf16 v[108:111], v[156:159], v[196:199], v[108:111]
	v_mfma_f32_16x16x32_bf16 v[104:107], v[164:167], v[196:199], v[104:107]
	v_mfma_f32_16x16x32_bf16 v[92:95], v[156:159], v[204:207], v[92:95]
	v_mfma_f32_16x16x32_bf16 v[88:91], v[164:167], v[204:207], v[88:91]
	v_mfma_f32_16x16x32_bf16 v[76:79], v[156:159], v[216:219], v[76:79]
	v_mfma_f32_16x16x32_bf16 v[72:75], v[164:167], v[216:219], v[72:75]
	s_setprio 0
	s_setprio 1
	v_mfma_f32_16x16x32_bf16 v[116:119], v[168:171], v[184:187], v[116:119]
	v_mfma_f32_16x16x32_bf16 v[112:115], v[176:179], v[184:187], v[112:115]
	v_mfma_f32_16x16x32_bf16 v[100:103], v[168:171], v[192:195], v[100:103]
	v_mfma_f32_16x16x32_bf16 v[96:99], v[176:179], v[192:195], v[96:99]
	v_mfma_f32_16x16x32_bf16 v[84:87], v[168:171], v[200:203], v[84:87]
	v_mfma_f32_16x16x32_bf16 v[80:83], v[176:179], v[200:203], v[80:83]
	v_mfma_f32_16x16x32_bf16 v[68:71], v[168:171], v[208:211], v[68:71]
	v_mfma_f32_16x16x32_bf16 v[64:67], v[176:179], v[208:211], v[64:67]
	v_mfma_f32_16x16x32_bf16 v[116:119], v[172:175], v[188:191], v[116:119]
	v_mfma_f32_16x16x32_bf16 v[112:115], v[180:183], v[188:191], v[112:115]
	v_mfma_f32_16x16x32_bf16 v[100:103], v[172:175], v[196:199], v[100:103]
	v_mfma_f32_16x16x32_bf16 v[96:99], v[180:183], v[196:199], v[96:99]
	v_mfma_f32_16x16x32_bf16 v[84:87], v[172:175], v[204:207], v[84:87]
	v_mfma_f32_16x16x32_bf16 v[80:83], v[180:183], v[204:207], v[80:83]
	v_mfma_f32_16x16x32_bf16 v[68:71], v[172:175], v[216:219], v[68:71]
	v_mfma_f32_16x16x32_bf16 v[64:67], v[180:183], v[216:219], v[64:67]
	s_setprio 0
	s_barrier
	s_add_i32 s2, s59, s40
	v_lshl_add_u64 v[148:149], v[148:149], 0, s[8:9]
	s_mov_b32 m0, s2
	ds_read_b128 v[184:187], v155 offset:49152
	ds_read_b128 v[188:191], v155 offset:50176
	ds_read_b128 v[192:195], v155 offset:51200
	ds_read_b128 v[196:199], v155 offset:52224
	ds_read_b128 v[200:203], v155 offset:53248
	ds_read_b128 v[204:207], v155 offset:54272
	ds_read_b128 v[208:211], v155 offset:55296
	ds_read_b128 v[216:219], v155 offset:56320
	global_load_lds_dwordx4 v[148:149], off
	s_add_i32 m0, s2, 0x2000
	s_add_u32 s2, s34, 0xb0080
	v_lshl_add_u64 v[148:149], v[212:213], 0, s[8:9]
	s_addc_u32 s3, s35, 0
	s_add_i32 s34, s60, s40
	global_load_lds_dwordx4 v[148:149], off
	v_lshl_add_u64 v[148:149], s[2:3], 0, v[130:131]
	s_mov_b32 m0, s34
	s_nop 0
	global_load_lds_dwordx4 v[148:149], off
	v_lshl_add_u64 v[148:149], s[2:3], 0, v[134:135]
	s_add_i32 m0, s34, 0x2000
	s_nop 0
	global_load_lds_dwordx4 v[148:149], off
	v_lshl_add_u64 v[148:149], v[220:221], 0, s[8:9]
	s_mov_b32 m0, s46
	s_nop 0
	global_load_lds_dwordx4 v[148:149], off
	v_lshl_add_u64 v[148:149], v[222:223], 0, s[8:9]
	s_mov_b32 m0, s47
	s_nop 0
	global_load_lds_dwordx4 v[148:149], off
	s_waitcnt vmcnt(8)
	s_waitcnt lgkmcnt(0)
	s_barrier
	s_setprio 1
	s_waitcnt lgkmcnt(0)
	v_mfma_f32_16x16x32_bf16 v[60:63], v[144:147], v[184:187], v[60:63]
	v_mfma_f32_16x16x32_bf16 v[56:59], v[160:163], v[184:187], v[56:59]
	v_mfma_f32_16x16x32_bf16 v[44:47], v[144:147], v[192:195], v[44:47]
	v_mfma_f32_16x16x32_bf16 v[40:43], v[160:163], v[192:195], v[40:43]
	v_mfma_f32_16x16x32_bf16 v[28:31], v[144:147], v[200:203], v[28:31]
	v_mfma_f32_16x16x32_bf16 v[24:27], v[160:163], v[200:203], v[24:27]
	v_mfma_f32_16x16x32_bf16 v[12:15], v[144:147], v[208:211], v[12:15]
	v_mfma_f32_16x16x32_bf16 v[8:11], v[160:163], v[208:211], v[8:11]
	v_mfma_f32_16x16x32_bf16 v[60:63], v[156:159], v[188:191], v[60:63]
	v_mfma_f32_16x16x32_bf16 v[56:59], v[164:167], v[188:191], v[56:59]
	v_mfma_f32_16x16x32_bf16 v[44:47], v[156:159], v[196:199], v[44:47]
	v_mfma_f32_16x16x32_bf16 v[40:43], v[164:167], v[196:199], v[40:43]
	v_mfma_f32_16x16x32_bf16 v[28:31], v[156:159], v[204:207], v[28:31]
	v_mfma_f32_16x16x32_bf16 v[24:27], v[164:167], v[204:207], v[24:27]
	v_mfma_f32_16x16x32_bf16 v[12:15], v[156:159], v[216:219], v[12:15]
	v_mfma_f32_16x16x32_bf16 v[8:11], v[164:167], v[216:219], v[8:11]
	s_setprio 0
	s_setprio 1
	v_mfma_f32_16x16x32_bf16 v[52:55], v[168:171], v[184:187], v[52:55]
	v_mfma_f32_16x16x32_bf16 v[48:51], v[176:179], v[184:187], v[48:51]
	v_mfma_f32_16x16x32_bf16 v[36:39], v[168:171], v[192:195], v[36:39]
	v_mfma_f32_16x16x32_bf16 v[32:35], v[176:179], v[192:195], v[32:35]
	v_mfma_f32_16x16x32_bf16 v[20:23], v[168:171], v[200:203], v[20:23]
	v_mfma_f32_16x16x32_bf16 v[16:19], v[176:179], v[200:203], v[16:19]
	v_mfma_f32_16x16x32_bf16 v[4:7], v[168:171], v[208:211], v[4:7]
	v_mfma_f32_16x16x32_bf16 v[0:3], v[176:179], v[208:211], v[0:3]
	v_mfma_f32_16x16x32_bf16 v[52:55], v[172:175], v[188:191], v[52:55]
	v_mfma_f32_16x16x32_bf16 v[48:51], v[180:183], v[188:191], v[48:51]
	v_mfma_f32_16x16x32_bf16 v[36:39], v[172:175], v[196:199], v[36:39]
	v_mfma_f32_16x16x32_bf16 v[32:35], v[180:183], v[196:199], v[32:35]
	v_mfma_f32_16x16x32_bf16 v[20:23], v[172:175], v[204:207], v[20:23]
	v_mfma_f32_16x16x32_bf16 v[16:19], v[180:183], v[204:207], v[16:19]
	v_mfma_f32_16x16x32_bf16 v[4:7], v[172:175], v[216:219], v[4:7]
	v_mfma_f32_16x16x32_bf16 v[0:3], v[180:183], v[216:219], v[0:3]
	s_setprio 0
	s_barrier
	s_add_i32 s58, s58, 2
	s_add_u32 s56, s56, 0x100
	s_addc_u32 s57, s57, 0
	s_cmp_gt_u32 s58, 41
	s_mov_b64 s[2:3], s[30:31]
	s_cbranch_scc0 .LBB0_1129
	s_and_b64 vcc, exec, s[10:11]
	s_cbranch_vccz .LBB0_1132
	s_barrier
